# removed the back-to-back s_setprio 0/1 pair from the middle of every 32-MFMA block in the four GEMM K-loops (two fewer issue slots between MFMAs)
# speedup vs baseline: 1.0075x; 1.0043x over previous
; #define PG8_STAGE(bufoff, gbase, voff) do { _Pragma("unroll") for (int _i = 0; _i < 2; ++_i) \
;         __builtin_amdgcn_global_load_lds((const unsigned*)((const char*)(gbase) + (voff)[_i]), (LAS unsigned*)(lds + (bufoff) + ldsw + _i * 8192), 16, 0, 0); } while (0)
; #define PG8_LDA(dst, b, h) do { _Pragma("unroll") for (int m = 0; m < 4; ++m) _Pragma("unroll") for (int k = 0; k < 2; ++k) dst[m][k] = *(const LAS bf16x8*)(lds + PG8_SA(b, h) + aoff + m * 2048 + k * 1024); } while (0)
; #define PG8_LDB(dst, b, h) do { _Pragma("unroll") for (int n = 0; n < 2; ++n) _Pragma("unroll") for (int k = 0; k < 2; ++k) dst[n][k] = *(const LAS bf16x8*)(lds + PG8_SB(b, h) + boff + n * 2048 + k * 1024); } while (0)
; #define PG8_WAIT_V(n) asm volatile("s_waitcnt vmcnt(" #n ")" ::: "memory")
; #define PG8_WAIT_L(n) asm volatile("s_waitcnt lgkmcnt(" #n ")" ::: "memory")
; #define PG8_BAR __builtin_amdgcn_s_barrier()
; #define PG8_SCHED __builtin_amdgcn_sched_barrier(0)
; template <class Epi, class Sched, bool ALIGN_EPI = false, bool SP2 = false>
; __device__ __forceinline__ void gemm_phase(LAS unsigned char* lds, const Gemm g, const Sched& S, const Epi& E) {
;     ...
;         const bool has_next = S.next(ui + 1, nxt);
;         const char* nA = has_next ? (const char*)g.A + (size_t)nxt.pm * tstep : cA; const char* nB = has_next ? (const char*)g.Bt + (size_t)nxt.pn * tstep : cB;
;         for (int t = 0; t < nt; t += 2) {
;             const bool last = (t == nt - 2);
;             const char* a1 = cA + (size_t)(t + 1) * kstep;
;             const char* a2 = last ? nA : cA + (size_t)(t + 2) * kstep; const char* b2 = last ? nB : cB + (size_t)(t + 2) * kstep;
;             const char* a3 = a2 + kstep; const char* b3 = b2 + kstep;
;             if (last && has_next) S.a_ready(nxt);
;             if constexpr (SP2) {
;             PG8_LDB(B0, 0, 0); PG8_LDB(B1, 0, 1); PG8_SCHED; PG8_LDA(At, 0, 0); PG8_STAGE(PG8_SA(1, 1), a1 + hstep, voffA);
;             PG8_WAIT_V(8); PG8_WAIT_L(0); PG8_BAR; PG8_MMA(0, 0, At, B0); PG8_MMA(0, 1, At, B1); PG8_BAR; PG8_SCHED;
;             PG8_LDA(At, 0, 1); PG8_STAGE(PG8_SB(0, 0), b2, voffB); PG8_STAGE(PG8_SB(0, 1), b2 + hstep, voffB); PG8_STAGE(PG8_SA(0, 0), a2, voffA);
;             PG8_WAIT_V(8); PG8_WAIT_L(0); PG8_BAR; PG8_MMA(1, 0, At, B0); PG8_MMA(1, 1, At, B1); PG8_BAR; PG8_SCHED;
.LBB0_122:
	s_add_u32 s14, s42, 0xfffc0080
	s_addc_u32 s15, s43, -1
	s_add_i32 vcc_hi, 0, 0x10000
	s_cmp_eq_u32 vcc_lo, 12
	s_cselect_b32 s97, s45, s15
	s_cselect_b32 s96, s51, s14
	s_cselect_b32 s47, s65, s99
	s_cselect_b32 s46, s76, s98
	s_add_i32 s16, 0, 0x14000
	v_add_u32_e32 v140, vcc_hi, v192
	v_add_u32_e32 v152, s16, v192
	s_waitcnt lgkmcnt(0)
	ds_read_b128 v[128:131], v140
	ds_read_b128 v[132:135], v140 offset:1024
	ds_read_b128 v[136:139], v140 offset:2048
	ds_read_b128 v[140:143], v140 offset:3072
	ds_read_b128 v[144:147], v152
	ds_read_b128 v[148:151], v152 offset:1024
	ds_read_b128 v[180:183], v152 offset:2048
	ds_read_b128 v[184:187], v152 offset:3072
	v_lshl_add_u64 v[204:205], s[42:43], 0, v[176:177]
	s_add_i32 m0, s93, 0xc000
	ds_read_b128 v[188:191], v194
	ds_read_b128 v[196:199], v194 offset:1024
	ds_read_b128 v[200:203], v194 offset:2048
	ds_read_b128 v[218:221], v194 offset:3072
	ds_read_b128 v[222:225], v194 offset:4096
	ds_read_b128 v[226:229], v194 offset:5120
	ds_read_b128 v[230:233], v194 offset:6144
	ds_read_b128 v[234:237], v194 offset:7168
	global_load_lds_dwordx4 v[204:205], off
	v_lshl_add_u64 v[204:205], s[42:43], 0, v[178:179]
	s_add_i32 m0, s93, 0xe000
	s_nop 0
	global_load_lds_dwordx4 v[204:205], off
	s_waitcnt vmcnt(8)
	s_waitcnt lgkmcnt(0)
	s_barrier
	s_setprio 1
	s_waitcnt lgkmcnt(0)
	v_mfma_f32_16x16x32_bf16 v[116:119], v[128:131], v[188:191], v[116:119]
	v_mfma_f32_16x16x32_bf16 v[112:115], v[136:139], v[188:191], v[112:115]
	v_mfma_f32_16x16x32_bf16 v[100:103], v[128:131], v[200:203], v[100:103]
	v_mfma_f32_16x16x32_bf16 v[96:99], v[136:139], v[200:203], v[96:99]
	v_mfma_f32_16x16x32_bf16 v[84:87], v[128:131], v[222:225], v[84:87]
	v_mfma_f32_16x16x32_bf16 v[80:83], v[136:139], v[222:225], v[80:83]
	v_mfma_f32_16x16x32_bf16 v[68:71], v[128:131], v[230:233], v[68:71]
	v_mfma_f32_16x16x32_bf16 v[64:67], v[136:139], v[230:233], v[64:67]
	v_mfma_f32_16x16x32_bf16 v[116:119], v[132:135], v[196:199], v[116:119]
	v_mfma_f32_16x16x32_bf16 v[112:115], v[140:143], v[196:199], v[112:115]
	v_mfma_f32_16x16x32_bf16 v[100:103], v[132:135], v[218:221], v[100:103]
	v_mfma_f32_16x16x32_bf16 v[96:99], v[140:143], v[218:221], v[96:99]
	v_mfma_f32_16x16x32_bf16 v[84:87], v[132:135], v[226:229], v[84:87]
	v_mfma_f32_16x16x32_bf16 v[80:83], v[140:143], v[226:229], v[80:83]
	v_mfma_f32_16x16x32_bf16 v[68:71], v[132:135], v[234:237], v[68:71]
	v_mfma_f32_16x16x32_bf16 v[64:67], v[140:143], v[234:237], v[64:67]
	v_mfma_f32_16x16x32_bf16 v[124:127], v[144:147], v[188:191], v[124:127]
	v_mfma_f32_16x16x32_bf16 v[120:123], v[180:183], v[188:191], v[120:123]
	v_mfma_f32_16x16x32_bf16 v[108:111], v[144:147], v[200:203], v[108:111]
	v_mfma_f32_16x16x32_bf16 v[104:107], v[180:183], v[200:203], v[104:107]
	v_mfma_f32_16x16x32_bf16 v[92:95], v[144:147], v[222:225], v[92:95]
	v_mfma_f32_16x16x32_bf16 v[88:91], v[180:183], v[222:225], v[88:91]
	v_mfma_f32_16x16x32_bf16 v[76:79], v[144:147], v[230:233], v[76:79]
	v_mfma_f32_16x16x32_bf16 v[72:75], v[180:183], v[230:233], v[72:75]
	v_mfma_f32_16x16x32_bf16 v[124:127], v[148:151], v[196:199], v[124:127]
	v_mfma_f32_16x16x32_bf16 v[120:123], v[184:187], v[196:199], v[120:123]
	v_mfma_f32_16x16x32_bf16 v[108:111], v[148:151], v[218:221], v[108:111]
	v_mfma_f32_16x16x32_bf16 v[104:107], v[184:187], v[218:221], v[104:107]
	v_mfma_f32_16x16x32_bf16 v[92:95], v[148:151], v[226:229], v[92:95]
	v_mfma_f32_16x16x32_bf16 v[88:91], v[184:187], v[226:229], v[88:91]
	v_mfma_f32_16x16x32_bf16 v[76:79], v[148:151], v[234:237], v[76:79]
	v_mfma_f32_16x16x32_bf16 v[72:75], v[184:187], v[234:237], v[72:75]
	s_setprio 0
	s_barrier
	s_add_i32 s14, vcc_hi, s73
	v_lshl_add_u64 v[204:205], s[46:47], 0, v[164:165]
	s_mov_b32 m0, s14
	ds_read_b128 v[188:191], v194 offset:16384
	ds_read_b128 v[196:199], v194 offset:17408
	ds_read_b128 v[200:203], v194 offset:18432
	ds_read_b128 v[218:221], v194 offset:19456
	ds_read_b128 v[222:225], v194 offset:20480
	ds_read_b128 v[226:229], v194 offset:21504
	ds_read_b128 v[230:233], v194 offset:22528
	ds_read_b128 v[234:237], v194 offset:23552
	global_load_lds_dwordx4 v[204:205], off
	s_add_i32 m0, s14, 0x2000
	s_add_u32 s14, s46, 0x40000
	v_lshl_add_u64 v[238:239], s[46:47], 0, v[168:169]
	s_addc_u32 s15, s47, 0
	s_add_i32 s16, s16, s73
	global_load_lds_dwordx4 v[238:239], off
	s_waitcnt vmcnt(4)
	s_waitcnt lgkmcnt(0)
	s_barrier
; #define PG8_STAGE(bufoff, gbase, voff) do { _Pragma("unroll") for (int _i = 0; _i < 2; ++_i) \
;         __builtin_amdgcn_global_load_lds((const unsigned*)((const char*)(gbase) + (voff)[_i]), (LAS unsigned*)(lds + (bufoff) + ldsw + _i * 8192), 16, 0, 0); } while (0)
; #define PG8_LDA(dst, b, h) do { _Pragma("unroll") for (int m = 0; m < 4; ++m) _Pragma("unroll") for (int k = 0; k < 2; ++k) dst[m][k] = *(const LAS bf16x8*)(lds + PG8_SA(b, h) + aoff + m * 2048 + k * 1024); } while (0)
; #define PG8_LDB(dst, b, h) do { _Pragma("unroll") for (int n = 0; n < 2; ++n) _Pragma("unroll") for (int k = 0; k < 2; ++k) dst[n][k] = *(const LAS bf16x8*)(lds + PG8_SB(b, h) + boff + n * 2048 + k * 1024); } while (0)
; #define PG8_MMA(ai, bj, At, Bt) do { __builtin_amdgcn_s_setprio(1); _Pragma("unroll") for (int m = 0; m < 4; ++m) _Pragma("unroll") for (int n = 0; n < 2; ++n) _Pragma("unroll") for (int k = 0; k < 2; ++k) \
;         acc[ai][bj][m][n] = __builtin_amdgcn_mfma_f32_16x16x32_bf16(Bt[n][k], At[m][k], acc[ai][bj][m][n], 0, 0, 0); __builtin_amdgcn_s_setprio(0); } while (0)
; #define PG8_WAIT_V(n) asm volatile("s_waitcnt vmcnt(" #n ")" ::: "memory")
; #define PG8_WAIT_L(n) asm volatile("s_waitcnt lgkmcnt(" #n ")" ::: "memory")
; #define PG8_BAR __builtin_amdgcn_s_barrier()
; #define PG8_SCHED __builtin_amdgcn_sched_barrier(0)
; template <class Epi, class Sched, bool ALIGN_EPI = false, bool SP2 = false>
; __device__ __forceinline__ void gemm_phase(LAS unsigned char* lds, const Gemm g, const Sched& S, const Epi& E) {
;     ...
;             PG8_WAIT_V(8); PG8_WAIT_L(0); PG8_BAR; PG8_MMA(1, 0, At, B0); PG8_MMA(1, 1, At, B1); PG8_BAR; PG8_SCHED;
;             PG8_LDB(B0, 1, 0); PG8_LDB(B1, 1, 1); PG8_SCHED; PG8_LDA(At, 1, 0); PG8_STAGE(PG8_SA(0, 1), a2 + hstep, voffA);
;             PG8_WAIT_V(8); PG8_WAIT_L(0); PG8_BAR; PG8_MMA(0, 0, At, B0); PG8_MMA(0, 1, At, B1); PG8_BAR; PG8_SCHED;
	s_setprio 1
	s_waitcnt lgkmcnt(0)
	v_mfma_f32_16x16x32_bf16 v[52:55], v[128:131], v[188:191], v[52:55]
	v_mfma_f32_16x16x32_bf16 v[48:51], v[136:139], v[188:191], v[48:51]
	v_mfma_f32_16x16x32_bf16 v[36:39], v[128:131], v[200:203], v[36:39]
	v_lshl_add_u64 v[240:241], s[14:15], 0, v[164:165]
	s_mov_b32 m0, s16
	v_lshl_add_u64 v[242:243], s[96:97], 0, v[166:167]
	v_mfma_f32_16x16x32_bf16 v[32:35], v[136:139], v[200:203], v[32:35]
	global_load_lds_dwordx4 v[240:241], off
	v_mfma_f32_16x16x32_bf16 v[20:23], v[128:131], v[222:225], v[20:23]
	v_mfma_f32_16x16x32_bf16 v[16:19], v[136:139], v[222:225], v[16:19]
	v_mfma_f32_16x16x32_bf16 v[4:7], v[128:131], v[230:233], v[4:7]
	v_mfma_f32_16x16x32_bf16 v[0:3], v[136:139], v[230:233], v[0:3]
	v_mfma_f32_16x16x32_bf16 v[52:55], v[132:135], v[196:199], v[52:55]
	v_mfma_f32_16x16x32_bf16 v[48:51], v[140:143], v[196:199], v[48:51]
	v_lshl_add_u64 v[240:241], s[14:15], 0, v[168:169]
	s_add_i32 m0, s16, 0x2000
	v_mfma_f32_16x16x32_bf16 v[36:39], v[132:135], v[218:221], v[36:39]
	global_load_lds_dwordx4 v[240:241], off
	v_mfma_f32_16x16x32_bf16 v[32:35], v[140:143], v[218:221], v[32:35]
	v_mfma_f32_16x16x32_bf16 v[20:23], v[132:135], v[226:229], v[20:23]
	v_mfma_f32_16x16x32_bf16 v[16:19], v[140:143], v[226:229], v[16:19]
	v_mfma_f32_16x16x32_bf16 v[4:7], v[132:135], v[234:237], v[4:7]
	v_mfma_f32_16x16x32_bf16 v[0:3], v[140:143], v[234:237], v[0:3]
	v_mfma_f32_16x16x32_bf16 v[60:63], v[144:147], v[188:191], v[60:63]
	v_mfma_f32_16x16x32_bf16 v[56:59], v[180:183], v[188:191], v[56:59]
	v_lshl_add_u64 v[240:241], s[96:97], 0, v[162:163]
	s_mov_b32 m0, s93
	v_mfma_f32_16x16x32_bf16 v[44:47], v[144:147], v[200:203], v[44:47]
	global_load_lds_dwordx4 v[240:241], off
	v_mfma_f32_16x16x32_bf16 v[40:43], v[180:183], v[200:203], v[40:43]
	v_mfma_f32_16x16x32_bf16 v[28:31], v[144:147], v[222:225], v[28:31]
	v_mfma_f32_16x16x32_bf16 v[24:27], v[180:183], v[222:225], v[24:27]
	v_mfma_f32_16x16x32_bf16 v[12:15], v[144:147], v[230:233], v[12:15]
	v_mfma_f32_16x16x32_bf16 v[8:11], v[180:183], v[230:233], v[8:11]
	v_mfma_f32_16x16x32_bf16 v[60:63], v[148:151], v[196:199], v[60:63]
	v_mfma_f32_16x16x32_bf16 v[56:59], v[184:187], v[196:199], v[56:59]
	s_mov_b32 m0, s4
	v_mfma_f32_16x16x32_bf16 v[44:47], v[148:151], v[218:221], v[44:47]
	global_load_lds_dwordx4 v[242:243], off
	v_mfma_f32_16x16x32_bf16 v[40:43], v[184:187], v[218:221], v[40:43]
	v_mfma_f32_16x16x32_bf16 v[28:31], v[148:151], v[226:229], v[28:31]
	v_mfma_f32_16x16x32_bf16 v[24:27], v[184:187], v[226:229], v[24:27]
	v_mfma_f32_16x16x32_bf16 v[12:15], v[148:151], v[234:237], v[12:15]
	v_mfma_f32_16x16x32_bf16 v[8:11], v[184:187], v[234:237], v[8:11]
	s_setprio 0
	s_barrier
	s_add_i32 s16, 0, 0x18000
	s_add_i32 s17, 0, 0x1c000
	v_add_u32_e32 v140, s16, v192
	v_add_u32_e32 v152, s17, v192
	ds_read_b128 v[128:131], v140
	ds_read_b128 v[132:135], v140 offset:1024
	ds_read_b128 v[136:139], v140 offset:2048
	ds_read_b128 v[140:143], v140 offset:3072
	ds_read_b128 v[144:147], v152
	ds_read_b128 v[148:151], v152 offset:1024
	ds_read_b128 v[180:183], v152 offset:2048
	ds_read_b128 v[184:187], v152 offset:3072
	s_add_u32 s14, s96, 0x40000
	s_addc_u32 s15, s97, 0
	s_mov_b32 m0, s5
	v_lshl_add_u64 v[244:245], s[14:15], 0, v[162:163]
	ds_read_b128 v[188:191], v194 offset:32768
	ds_read_b128 v[196:199], v194 offset:33792
	ds_read_b128 v[200:203], v194 offset:34816
	ds_read_b128 v[218:221], v194 offset:35840
	ds_read_b128 v[222:225], v194 offset:36864
	ds_read_b128 v[226:229], v194 offset:37888
	ds_read_b128 v[230:233], v194 offset:38912
	ds_read_b128 v[234:237], v194 offset:39936
	global_load_lds_dwordx4 v[244:245], off
	v_lshl_add_u64 v[244:245], s[14:15], 0, v[166:167]
	s_mov_b32 m0, s6
	s_nop 0
	global_load_lds_dwordx4 v[244:245], off
	s_waitcnt vmcnt(8)
	s_waitcnt lgkmcnt(0)
	s_barrier
; #define PG8_STAGE(bufoff, gbase, voff) do { _Pragma("unroll") for (int _i = 0; _i < 2; ++_i) \
;         __builtin_amdgcn_global_load_lds((const unsigned*)((const char*)(gbase) + (voff)[_i]), (LAS unsigned*)(lds + (bufoff) + ldsw + _i * 8192), 16, 0, 0); } while (0)
; #define PG8_LDA(dst, b, h) do { _Pragma("unroll") for (int m = 0; m < 4; ++m) _Pragma("unroll") for (int k = 0; k < 2; ++k) dst[m][k] = *(const LAS bf16x8*)(lds + PG8_SA(b, h) + aoff + m * 2048 + k * 1024); } while (0)
; #define PG8_MMA(ai, bj, At, Bt) do { __builtin_amdgcn_s_setprio(1); _Pragma("unroll") for (int m = 0; m < 4; ++m) _Pragma("unroll") for (int n = 0; n < 2; ++n) _Pragma("unroll") for (int k = 0; k < 2; ++k) \
;         acc[ai][bj][m][n] = __builtin_amdgcn_mfma_f32_16x16x32_bf16(Bt[n][k], At[m][k], acc[ai][bj][m][n], 0, 0, 0); __builtin_amdgcn_s_setprio(0); } while (0)
; #define PG8_WAIT_V(n) asm volatile("s_waitcnt vmcnt(" #n ")" ::: "memory")
; #define PG8_WAIT_L(n) asm volatile("s_waitcnt lgkmcnt(" #n ")" ::: "memory")
; #define PG8_BAR __builtin_amdgcn_s_barrier()
; #define PG8_SCHED __builtin_amdgcn_sched_barrier(0)
; template <class Epi, class Sched, bool ALIGN_EPI = false, bool SP2 = false>
; __device__ __forceinline__ void gemm_phase(LAS unsigned char* lds, const Gemm g, const Sched& S, const Epi& E) {
;     ...
;             PG8_WAIT_V(8); PG8_WAIT_L(0); PG8_BAR; PG8_MMA(0, 0, At, B0); PG8_MMA(0, 1, At, B1); PG8_BAR; PG8_SCHED;
;             PG8_LDA(At, 1, 1); PG8_STAGE(PG8_SB(1, 0), b3, voffB); PG8_STAGE(PG8_SB(1, 1), b3 + hstep, voffB); PG8_STAGE(PG8_SA(1, 0), a3, voffA);
;             PG8_WAIT_V(8); PG8_WAIT_L(0); PG8_BAR; PG8_MMA(1, 0, At, B0); PG8_MMA(1, 1, At, B1); PG8_BAR; PG8_SCHED;
;     ...
;         if constexpr (ALIGN_EPI) { if (wr == 0) PG8_BAR; }
	s_setprio 1
	s_waitcnt lgkmcnt(0)
	v_mfma_f32_16x16x32_bf16 v[116:119], v[128:131], v[188:191], v[116:119]
	v_mfma_f32_16x16x32_bf16 v[112:115], v[136:139], v[188:191], v[112:115]
	v_mfma_f32_16x16x32_bf16 v[100:103], v[128:131], v[200:203], v[100:103]
	v_mfma_f32_16x16x32_bf16 v[96:99], v[136:139], v[200:203], v[96:99]
	v_mfma_f32_16x16x32_bf16 v[84:87], v[128:131], v[222:225], v[84:87]
	v_mfma_f32_16x16x32_bf16 v[80:83], v[136:139], v[222:225], v[80:83]
	v_mfma_f32_16x16x32_bf16 v[68:71], v[128:131], v[230:233], v[68:71]
	v_mfma_f32_16x16x32_bf16 v[64:67], v[136:139], v[230:233], v[64:67]
	v_mfma_f32_16x16x32_bf16 v[116:119], v[132:135], v[196:199], v[116:119]
	v_mfma_f32_16x16x32_bf16 v[112:115], v[140:143], v[196:199], v[112:115]
	v_mfma_f32_16x16x32_bf16 v[100:103], v[132:135], v[218:221], v[100:103]
	v_mfma_f32_16x16x32_bf16 v[96:99], v[140:143], v[218:221], v[96:99]
	v_mfma_f32_16x16x32_bf16 v[84:87], v[132:135], v[226:229], v[84:87]
	v_mfma_f32_16x16x32_bf16 v[80:83], v[140:143], v[226:229], v[80:83]
	v_mfma_f32_16x16x32_bf16 v[68:71], v[132:135], v[234:237], v[68:71]
	v_mfma_f32_16x16x32_bf16 v[64:67], v[140:143], v[234:237], v[64:67]
	v_mfma_f32_16x16x32_bf16 v[124:127], v[144:147], v[188:191], v[124:127]
	v_mfma_f32_16x16x32_bf16 v[120:123], v[180:183], v[188:191], v[120:123]
	v_mfma_f32_16x16x32_bf16 v[108:111], v[144:147], v[200:203], v[108:111]
	v_mfma_f32_16x16x32_bf16 v[104:107], v[180:183], v[200:203], v[104:107]
	v_mfma_f32_16x16x32_bf16 v[92:95], v[144:147], v[222:225], v[92:95]
	v_mfma_f32_16x16x32_bf16 v[88:91], v[180:183], v[222:225], v[88:91]
	v_mfma_f32_16x16x32_bf16 v[76:79], v[144:147], v[230:233], v[76:79]
	v_mfma_f32_16x16x32_bf16 v[72:75], v[180:183], v[230:233], v[72:75]
	v_mfma_f32_16x16x32_bf16 v[124:127], v[148:151], v[196:199], v[124:127]
	v_mfma_f32_16x16x32_bf16 v[120:123], v[184:187], v[196:199], v[120:123]
	v_mfma_f32_16x16x32_bf16 v[108:111], v[148:151], v[218:221], v[108:111]
	v_mfma_f32_16x16x32_bf16 v[104:107], v[184:187], v[218:221], v[104:107]
	v_mfma_f32_16x16x32_bf16 v[92:95], v[148:151], v[226:229], v[92:95]
	v_mfma_f32_16x16x32_bf16 v[88:91], v[184:187], v[226:229], v[88:91]
	v_mfma_f32_16x16x32_bf16 v[76:79], v[148:151], v[234:237], v[76:79]
	v_mfma_f32_16x16x32_bf16 v[72:75], v[184:187], v[234:237], v[72:75]
	s_setprio 0
	s_barrier
	s_add_i32 s14, s16, s73
	v_lshl_add_u64 v[204:205], v[204:205], 0, s[30:31]
	s_mov_b32 m0, s14
	ds_read_b128 v[188:191], v194 offset:49152
	ds_read_b128 v[196:199], v194 offset:50176
	ds_read_b128 v[200:203], v194 offset:51200
	ds_read_b128 v[218:221], v194 offset:52224
	ds_read_b128 v[222:225], v194 offset:53248
	ds_read_b128 v[226:229], v194 offset:54272
	ds_read_b128 v[230:233], v194 offset:55296
	ds_read_b128 v[234:237], v194 offset:56320
	global_load_lds_dwordx4 v[204:205], off
	s_add_i32 m0, s14, 0x2000
	s_add_u32 s14, s46, 0x40080
	v_lshl_add_u64 v[204:205], v[238:239], 0, s[30:31]
	s_addc_u32 s15, s47, 0
	s_add_i32 s16, s17, s73
	global_load_lds_dwordx4 v[204:205], off
	s_waitcnt vmcnt(4)
	s_waitcnt lgkmcnt(0)
	s_barrier
	s_setprio 1
	s_waitcnt lgkmcnt(0)
	v_mfma_f32_16x16x32_bf16 v[52:55], v[128:131], v[188:191], v[52:55]
	v_mfma_f32_16x16x32_bf16 v[48:51], v[136:139], v[188:191], v[48:51]
	v_mfma_f32_16x16x32_bf16 v[36:39], v[128:131], v[200:203], v[36:39]
	v_lshl_add_u64 v[204:205], s[14:15], 0, v[164:165]
	s_mov_b32 m0, s16
	v_mfma_f32_16x16x32_bf16 v[32:35], v[136:139], v[200:203], v[32:35]
	global_load_lds_dwordx4 v[204:205], off
	v_mfma_f32_16x16x32_bf16 v[20:23], v[128:131], v[222:225], v[20:23]
	v_mfma_f32_16x16x32_bf16 v[16:19], v[136:139], v[222:225], v[16:19]
	v_mfma_f32_16x16x32_bf16 v[4:7], v[128:131], v[230:233], v[4:7]
	v_mfma_f32_16x16x32_bf16 v[0:3], v[136:139], v[230:233], v[0:3]
	v_mfma_f32_16x16x32_bf16 v[52:55], v[132:135], v[196:199], v[52:55]
	v_mfma_f32_16x16x32_bf16 v[48:51], v[140:143], v[196:199], v[48:51]
	v_lshl_add_u64 v[204:205], s[14:15], 0, v[168:169]
	s_add_i32 m0, s16, 0x2000
	v_mfma_f32_16x16x32_bf16 v[36:39], v[132:135], v[218:221], v[36:39]
	global_load_lds_dwordx4 v[204:205], off
	v_mfma_f32_16x16x32_bf16 v[32:35], v[140:143], v[218:221], v[32:35]
	v_mfma_f32_16x16x32_bf16 v[20:23], v[132:135], v[226:229], v[20:23]
	v_mfma_f32_16x16x32_bf16 v[16:19], v[140:143], v[226:229], v[16:19]
	v_mfma_f32_16x16x32_bf16 v[4:7], v[132:135], v[234:237], v[4:7]
	v_mfma_f32_16x16x32_bf16 v[0:3], v[140:143], v[234:237], v[0:3]
	v_mfma_f32_16x16x32_bf16 v[60:63], v[144:147], v[188:191], v[60:63]
	v_mfma_f32_16x16x32_bf16 v[56:59], v[180:183], v[188:191], v[56:59]
	v_lshl_add_u64 v[204:205], v[240:241], 0, s[30:31]
	s_mov_b32 m0, s8
	v_mfma_f32_16x16x32_bf16 v[44:47], v[144:147], v[200:203], v[44:47]
	global_load_lds_dwordx4 v[204:205], off
	v_mfma_f32_16x16x32_bf16 v[40:43], v[180:183], v[200:203], v[40:43]
	v_mfma_f32_16x16x32_bf16 v[28:31], v[144:147], v[222:225], v[28:31]
	v_mfma_f32_16x16x32_bf16 v[24:27], v[180:183], v[222:225], v[24:27]
	v_mfma_f32_16x16x32_bf16 v[12:15], v[144:147], v[230:233], v[12:15]
	v_mfma_f32_16x16x32_bf16 v[8:11], v[180:183], v[230:233], v[8:11]
	v_mfma_f32_16x16x32_bf16 v[60:63], v[148:151], v[196:199], v[60:63]
	v_mfma_f32_16x16x32_bf16 v[56:59], v[184:187], v[196:199], v[56:59]
	v_lshl_add_u64 v[204:205], v[242:243], 0, s[30:31]
	s_mov_b32 m0, s9
	v_mfma_f32_16x16x32_bf16 v[44:47], v[148:151], v[218:221], v[44:47]
	global_load_lds_dwordx4 v[204:205], off
	v_mfma_f32_16x16x32_bf16 v[40:43], v[184:187], v[218:221], v[40:43]
	v_mfma_f32_16x16x32_bf16 v[28:31], v[148:151], v[226:229], v[28:31]
	v_mfma_f32_16x16x32_bf16 v[24:27], v[184:187], v[226:229], v[24:27]
	v_mfma_f32_16x16x32_bf16 v[12:15], v[148:151], v[234:237], v[12:15]
	v_mfma_f32_16x16x32_bf16 v[8:11], v[184:187], v[234:237], v[8:11]
	s_setprio 0
	s_barrier
	s_add_i32 vcc_lo, vcc_lo, 2
	s_add_u32 s42, s42, 0x100
	s_addc_u32 s43, s43, 0
	s_add_u32 s98, s98, 0x100
	s_addc_u32 s99, s99, 0
	s_cmp_gt_u32 vcc_lo, 13
	s_cbranch_scc0 .LBB0_122
	s_and_b64 vcc, exec, s[38:39]
	s_cbranch_vccz .LBB0_125
	s_barrier

; #define PG8_STAGE(bufoff, gbase, voff) do { _Pragma("unroll") for (int _i = 0; _i < 2; ++_i) \
;         __builtin_amdgcn_global_load_lds((const unsigned*)((const char*)(gbase) + (voff)[_i]), (LAS unsigned*)(lds + (bufoff) + ldsw + _i * 8192), 16, 0, 0); } while (0)
; #define PG8_LDA(dst, b, h) do { _Pragma("unroll") for (int m = 0; m < 4; ++m) _Pragma("unroll") for (int k = 0; k < 2; ++k) dst[m][k] = *(const LAS bf16x8*)(lds + PG8_SA(b, h) + aoff + m * 2048 + k * 1024); } while (0)
; #define PG8_LDB(dst, b, h) do { _Pragma("unroll") for (int n = 0; n < 2; ++n) _Pragma("unroll") for (int k = 0; k < 2; ++k) dst[n][k] = *(const LAS bf16x8*)(lds + PG8_SB(b, h) + boff + n * 2048 + k * 1024); } while (0)
; #define PG8_WAIT_V(n) asm volatile("s_waitcnt vmcnt(" #n ")" ::: "memory")
; #define PG8_WAIT_L(n) asm volatile("s_waitcnt lgkmcnt(" #n ")" ::: "memory")
; #define PG8_BAR __builtin_amdgcn_s_barrier()
; #define PG8_SCHED __builtin_amdgcn_sched_barrier(0)
; template <class Epi, class Sched, bool ALIGN_EPI = false, bool SP2 = false>
; __device__ __forceinline__ void gemm_phase(LAS unsigned char* lds, const Gemm g, const Sched& S, const Epi& E) {
;     ...
;         const bool has_next = S.next(ui + 1, nxt);
;         const char* nA = has_next ? (const char*)g.A + (size_t)nxt.pm * tstep : cA; const char* nB = has_next ? (const char*)g.Bt + (size_t)nxt.pn * tstep : cB;
;         for (int t = 0; t < nt; t += 2) {
;             const bool last = (t == nt - 2);
;             const char* a1 = cA + (size_t)(t + 1) * kstep;
;             const char* a2 = last ? nA : cA + (size_t)(t + 2) * kstep; const char* b2 = last ? nB : cB + (size_t)(t + 2) * kstep;
;             const char* a3 = a2 + kstep; const char* b3 = b2 + kstep;
;             if (last && has_next) S.a_ready(nxt);
;             if constexpr (SP2) {
;             PG8_LDB(B0, 0, 0); PG8_LDB(B1, 0, 1); PG8_SCHED; PG8_LDA(At, 0, 0); PG8_STAGE(PG8_SA(1, 1), a1 + hstep, voffA);
;             PG8_WAIT_V(8); PG8_WAIT_L(0); PG8_BAR; PG8_MMA(0, 0, At, B0); PG8_MMA(0, 1, At, B1); PG8_BAR; PG8_SCHED;
;             PG8_LDA(At, 0, 1); PG8_STAGE(PG8_SB(0, 0), b2, voffB); PG8_STAGE(PG8_SB(0, 1), b2 + hstep, voffB); PG8_STAGE(PG8_SA(0, 0), a2, voffA);
;             PG8_WAIT_V(8); PG8_WAIT_L(0); PG8_BAR; PG8_MMA(1, 0, At, B0); PG8_MMA(1, 1, At, B1); PG8_BAR; PG8_SCHED;
.LBB0_418:
	s_add_u32 s13, s24, 0xfffc0080
	s_addc_u32 s14, s25, -1
	s_add_i32 s15, 0, 0x10000
	s_cmp_eq_u32 s12, 12
	s_cselect_b32 s39, s6, s14
	s_cselect_b32 s38, s7, s13
	s_cselect_b32 s37, s8, s11
	s_cselect_b32 s36, s9, s10
	s_add_i32 s13, 0, 0x14000
	v_add_u32_e32 v140, s15, v218
	v_add_u32_e32 v152, s13, v218
	ds_read_b128 v[128:131], v140
	ds_read_b128 v[132:135], v140 offset:1024
	ds_read_b128 v[136:139], v140 offset:2048
	ds_read_b128 v[140:143], v140 offset:3072
	ds_read_b128 v[166:169], v152
	ds_read_b128 v[170:173], v152 offset:1024
	ds_read_b128 v[174:177], v152 offset:2048
	ds_read_b128 v[178:181], v152 offset:3072
	v_lshl_add_u64 v[230:231], s[24:25], 0, v[162:163]
	s_add_i32 m0, s71, 0xc000
	ds_read_b128 v[182:185], v221
	ds_read_b128 v[186:189], v221 offset:1024
	ds_read_b128 v[190:193], v221 offset:2048
	ds_read_b128 v[194:197], v221 offset:3072
	ds_read_b128 v[198:201], v221 offset:4096
	ds_read_b128 v[202:205], v221 offset:5120
	ds_read_b128 v[222:225], v221 offset:6144
	ds_read_b128 v[226:229], v221 offset:7168
	global_load_lds_dwordx4 v[230:231], off
	v_lshl_add_u64 v[230:231], s[24:25], 0, v[164:165]
	s_add_i32 m0, s71, 0xe000
	s_nop 0
	global_load_lds_dwordx4 v[230:231], off
	s_waitcnt vmcnt(8)
	s_waitcnt lgkmcnt(0)
	s_barrier
	s_setprio 1
	s_waitcnt lgkmcnt(0)
	v_mfma_f32_16x16x32_bf16 v[124:127], v[128:131], v[182:185], v[124:127]
	v_mfma_f32_16x16x32_bf16 v[120:123], v[136:139], v[182:185], v[120:123]
	v_mfma_f32_16x16x32_bf16 v[108:111], v[128:131], v[190:193], v[108:111]
	v_mfma_f32_16x16x32_bf16 v[104:107], v[136:139], v[190:193], v[104:107]
	v_mfma_f32_16x16x32_bf16 v[92:95], v[128:131], v[198:201], v[92:95]
	v_mfma_f32_16x16x32_bf16 v[88:91], v[136:139], v[198:201], v[88:91]
	v_mfma_f32_16x16x32_bf16 v[76:79], v[128:131], v[222:225], v[76:79]
	v_mfma_f32_16x16x32_bf16 v[72:75], v[136:139], v[222:225], v[72:75]
	v_mfma_f32_16x16x32_bf16 v[124:127], v[132:135], v[186:189], v[124:127]
	v_mfma_f32_16x16x32_bf16 v[120:123], v[140:143], v[186:189], v[120:123]
	v_mfma_f32_16x16x32_bf16 v[108:111], v[132:135], v[194:197], v[108:111]
	v_mfma_f32_16x16x32_bf16 v[104:107], v[140:143], v[194:197], v[104:107]
	v_mfma_f32_16x16x32_bf16 v[92:95], v[132:135], v[202:205], v[92:95]
	v_mfma_f32_16x16x32_bf16 v[88:91], v[140:143], v[202:205], v[88:91]
	v_mfma_f32_16x16x32_bf16 v[76:79], v[132:135], v[226:229], v[76:79]
	v_mfma_f32_16x16x32_bf16 v[72:75], v[140:143], v[226:229], v[72:75]
	v_mfma_f32_16x16x32_bf16 v[116:119], v[166:169], v[182:185], v[116:119]
	v_mfma_f32_16x16x32_bf16 v[112:115], v[174:177], v[182:185], v[112:115]
	v_mfma_f32_16x16x32_bf16 v[100:103], v[166:169], v[190:193], v[100:103]
	v_mfma_f32_16x16x32_bf16 v[96:99], v[174:177], v[190:193], v[96:99]
	v_mfma_f32_16x16x32_bf16 v[84:87], v[166:169], v[198:201], v[84:87]
	v_mfma_f32_16x16x32_bf16 v[80:83], v[174:177], v[198:201], v[80:83]
	v_mfma_f32_16x16x32_bf16 v[68:71], v[166:169], v[222:225], v[68:71]
	v_mfma_f32_16x16x32_bf16 v[64:67], v[174:177], v[222:225], v[64:67]
	v_mfma_f32_16x16x32_bf16 v[116:119], v[170:173], v[186:189], v[116:119]
	v_mfma_f32_16x16x32_bf16 v[112:115], v[178:181], v[186:189], v[112:115]
	v_mfma_f32_16x16x32_bf16 v[100:103], v[170:173], v[194:197], v[100:103]
	v_mfma_f32_16x16x32_bf16 v[96:99], v[178:181], v[194:197], v[96:99]
	v_mfma_f32_16x16x32_bf16 v[84:87], v[170:173], v[202:205], v[84:87]
	v_mfma_f32_16x16x32_bf16 v[80:83], v[178:181], v[202:205], v[80:83]
	v_mfma_f32_16x16x32_bf16 v[68:71], v[170:173], v[226:229], v[68:71]
	v_mfma_f32_16x16x32_bf16 v[64:67], v[178:181], v[226:229], v[64:67]
	s_setprio 0
	s_barrier
	s_add_i32 s14, s15, s70
	v_lshl_add_u64 v[230:231], s[36:37], 0, v[148:149]
	s_mov_b32 m0, s14
	ds_read_b128 v[182:185], v221 offset:16384
	ds_read_b128 v[186:189], v221 offset:17408
	ds_read_b128 v[190:193], v221 offset:18432
	ds_read_b128 v[194:197], v221 offset:19456
	ds_read_b128 v[198:201], v221 offset:20480
	ds_read_b128 v[202:205], v221 offset:21504
	ds_read_b128 v[222:225], v221 offset:22528
	ds_read_b128 v[226:229], v221 offset:23552
	global_load_lds_dwordx4 v[230:231], off
	s_add_i32 m0, s14, 0x2000
	s_add_u32 s14, s36, 0x40000
	v_lshl_add_u64 v[232:233], s[36:37], 0, v[144:145]
	s_addc_u32 s15, s37, 0
	s_add_i32 s13, s13, s70
	global_load_lds_dwordx4 v[232:233], off
	s_waitcnt vmcnt(4)
	s_waitcnt lgkmcnt(0)
	s_barrier
; #define PG8_STAGE(bufoff, gbase, voff) do { _Pragma("unroll") for (int _i = 0; _i < 2; ++_i) \
;         __builtin_amdgcn_global_load_lds((const unsigned*)((const char*)(gbase) + (voff)[_i]), (LAS unsigned*)(lds + (bufoff) + ldsw + _i * 8192), 16, 0, 0); } while (0)
; #define PG8_LDA(dst, b, h) do { _Pragma("unroll") for (int m = 0; m < 4; ++m) _Pragma("unroll") for (int k = 0; k < 2; ++k) dst[m][k] = *(const LAS bf16x8*)(lds + PG8_SA(b, h) + aoff + m * 2048 + k * 1024); } while (0)
; #define PG8_LDB(dst, b, h) do { _Pragma("unroll") for (int n = 0; n < 2; ++n) _Pragma("unroll") for (int k = 0; k < 2; ++k) dst[n][k] = *(const LAS bf16x8*)(lds + PG8_SB(b, h) + boff + n * 2048 + k * 1024); } while (0)
; #define PG8_MMA(ai, bj, At, Bt) do { __builtin_amdgcn_s_setprio(1); _Pragma("unroll") for (int m = 0; m < 4; ++m) _Pragma("unroll") for (int n = 0; n < 2; ++n) _Pragma("unroll") for (int k = 0; k < 2; ++k) \
;         acc[ai][bj][m][n] = __builtin_amdgcn_mfma_f32_16x16x32_bf16(Bt[n][k], At[m][k], acc[ai][bj][m][n], 0, 0, 0); __builtin_amdgcn_s_setprio(0); } while (0)
; #define PG8_WAIT_V(n) asm volatile("s_waitcnt vmcnt(" #n ")" ::: "memory")
; #define PG8_WAIT_L(n) asm volatile("s_waitcnt lgkmcnt(" #n ")" ::: "memory")
; #define PG8_BAR __builtin_amdgcn_s_barrier()
; #define PG8_SCHED __builtin_amdgcn_sched_barrier(0)
; template <class Epi, class Sched, bool ALIGN_EPI = false, bool SP2 = false>
; __device__ __forceinline__ void gemm_phase(LAS unsigned char* lds, const Gemm g, const Sched& S, const Epi& E) {
;     ...
;             PG8_WAIT_V(8); PG8_WAIT_L(0); PG8_BAR; PG8_MMA(1, 0, At, B0); PG8_MMA(1, 1, At, B1); PG8_BAR; PG8_SCHED;
;             PG8_LDB(B0, 1, 0); PG8_LDB(B1, 1, 1); PG8_SCHED; PG8_LDA(At, 1, 0); PG8_STAGE(PG8_SA(0, 1), a2 + hstep, voffA);
;             PG8_WAIT_V(8); PG8_WAIT_L(0); PG8_BAR; PG8_MMA(0, 0, At, B0); PG8_MMA(0, 1, At, B1); PG8_BAR; PG8_SCHED;
	s_setprio 1
	s_waitcnt lgkmcnt(0)
	v_mfma_f32_16x16x32_bf16 v[60:63], v[128:131], v[182:185], v[60:63]
	v_mfma_f32_16x16x32_bf16 v[56:59], v[136:139], v[182:185], v[56:59]
	v_mfma_f32_16x16x32_bf16 v[44:47], v[128:131], v[190:193], v[44:47]
	v_lshl_add_u64 v[234:235], s[14:15], 0, v[148:149]
	s_mov_b32 m0, s13
	v_lshl_add_u64 v[236:237], s[38:39], 0, v[146:147]
	v_mfma_f32_16x16x32_bf16 v[40:43], v[136:139], v[190:193], v[40:43]
	global_load_lds_dwordx4 v[234:235], off
	v_mfma_f32_16x16x32_bf16 v[28:31], v[128:131], v[198:201], v[28:31]
	v_mfma_f32_16x16x32_bf16 v[24:27], v[136:139], v[198:201], v[24:27]
	v_mfma_f32_16x16x32_bf16 v[12:15], v[128:131], v[222:225], v[12:15]
	v_mfma_f32_16x16x32_bf16 v[8:11], v[136:139], v[222:225], v[8:11]
	v_mfma_f32_16x16x32_bf16 v[60:63], v[132:135], v[186:189], v[60:63]
	v_mfma_f32_16x16x32_bf16 v[56:59], v[140:143], v[186:189], v[56:59]
	v_lshl_add_u64 v[234:235], s[14:15], 0, v[144:145]
	s_add_i32 m0, s13, 0x2000
	v_mfma_f32_16x16x32_bf16 v[44:47], v[132:135], v[194:197], v[44:47]
	global_load_lds_dwordx4 v[234:235], off
	v_mfma_f32_16x16x32_bf16 v[40:43], v[140:143], v[194:197], v[40:43]
	v_mfma_f32_16x16x32_bf16 v[28:31], v[132:135], v[202:205], v[28:31]
	v_mfma_f32_16x16x32_bf16 v[24:27], v[140:143], v[202:205], v[24:27]
	v_mfma_f32_16x16x32_bf16 v[12:15], v[132:135], v[226:229], v[12:15]
	v_mfma_f32_16x16x32_bf16 v[8:11], v[140:143], v[226:229], v[8:11]
	v_mfma_f32_16x16x32_bf16 v[52:55], v[166:169], v[182:185], v[52:55]
	v_mfma_f32_16x16x32_bf16 v[48:51], v[174:177], v[182:185], v[48:51]
	v_lshl_add_u64 v[234:235], s[38:39], 0, v[150:151]
	s_mov_b32 m0, s71
	v_mfma_f32_16x16x32_bf16 v[36:39], v[166:169], v[190:193], v[36:39]
	global_load_lds_dwordx4 v[234:235], off
	v_mfma_f32_16x16x32_bf16 v[32:35], v[174:177], v[190:193], v[32:35]
	v_mfma_f32_16x16x32_bf16 v[20:23], v[166:169], v[198:201], v[20:23]
	v_mfma_f32_16x16x32_bf16 v[16:19], v[174:177], v[198:201], v[16:19]
	v_mfma_f32_16x16x32_bf16 v[4:7], v[166:169], v[222:225], v[4:7]
	v_mfma_f32_16x16x32_bf16 v[0:3], v[174:177], v[222:225], v[0:3]
	v_mfma_f32_16x16x32_bf16 v[52:55], v[170:173], v[186:189], v[52:55]
	v_mfma_f32_16x16x32_bf16 v[48:51], v[178:181], v[186:189], v[48:51]
	s_mov_b32 m0, s76
	v_mfma_f32_16x16x32_bf16 v[36:39], v[170:173], v[194:197], v[36:39]
	global_load_lds_dwordx4 v[236:237], off
	v_mfma_f32_16x16x32_bf16 v[32:35], v[178:181], v[194:197], v[32:35]
	v_mfma_f32_16x16x32_bf16 v[20:23], v[170:173], v[202:205], v[20:23]
	v_mfma_f32_16x16x32_bf16 v[16:19], v[178:181], v[202:205], v[16:19]
	v_mfma_f32_16x16x32_bf16 v[4:7], v[170:173], v[226:229], v[4:7]
	v_mfma_f32_16x16x32_bf16 v[0:3], v[178:181], v[226:229], v[0:3]
	s_setprio 0
	s_barrier
	s_add_i32 s13, 0, 0x18000
	s_add_i32 s16, 0, 0x1c000
	v_add_u32_e32 v140, s13, v218
	v_add_u32_e32 v152, s16, v218
	ds_read_b128 v[128:131], v140
	ds_read_b128 v[132:135], v140 offset:1024
	ds_read_b128 v[136:139], v140 offset:2048
	ds_read_b128 v[140:143], v140 offset:3072
	ds_read_b128 v[166:169], v152
	ds_read_b128 v[170:173], v152 offset:1024
	ds_read_b128 v[174:177], v152 offset:2048
	ds_read_b128 v[178:181], v152 offset:3072
	s_add_u32 s14, s38, 0x40000
	s_addc_u32 s15, s39, 0
	s_mov_b32 m0, s92
	v_lshl_add_u64 v[238:239], s[14:15], 0, v[150:151]
	ds_read_b128 v[182:185], v221 offset:32768
	ds_read_b128 v[186:189], v221 offset:33792
	ds_read_b128 v[190:193], v221 offset:34816
	ds_read_b128 v[194:197], v221 offset:35840
	ds_read_b128 v[198:201], v221 offset:36864
	ds_read_b128 v[202:205], v221 offset:37888
	ds_read_b128 v[222:225], v221 offset:38912
	ds_read_b128 v[226:229], v221 offset:39936
	global_load_lds_dwordx4 v[238:239], off
	v_lshl_add_u64 v[238:239], s[14:15], 0, v[146:147]
	s_mov_b32 m0, s93
	s_nop 0
	global_load_lds_dwordx4 v[238:239], off
	s_waitcnt vmcnt(8)
	s_waitcnt lgkmcnt(0)
	s_barrier
; #define PG8_STAGE(bufoff, gbase, voff) do { _Pragma("unroll") for (int _i = 0; _i < 2; ++_i) \
;         __builtin_amdgcn_global_load_lds((const unsigned*)((const char*)(gbase) + (voff)[_i]), (LAS unsigned*)(lds + (bufoff) + ldsw + _i * 8192), 16, 0, 0); } while (0)
; #define PG8_LDA(dst, b, h) do { _Pragma("unroll") for (int m = 0; m < 4; ++m) _Pragma("unroll") for (int k = 0; k < 2; ++k) dst[m][k] = *(const LAS bf16x8*)(lds + PG8_SA(b, h) + aoff + m * 2048 + k * 1024); } while (0)
; #define PG8_MMA(ai, bj, At, Bt) do { __builtin_amdgcn_s_setprio(1); _Pragma("unroll") for (int m = 0; m < 4; ++m) _Pragma("unroll") for (int n = 0; n < 2; ++n) _Pragma("unroll") for (int k = 0; k < 2; ++k) \
;         acc[ai][bj][m][n] = __builtin_amdgcn_mfma_f32_16x16x32_bf16(Bt[n][k], At[m][k], acc[ai][bj][m][n], 0, 0, 0); __builtin_amdgcn_s_setprio(0); } while (0)
; #define PG8_WAIT_V(n) asm volatile("s_waitcnt vmcnt(" #n ")" ::: "memory")
; #define PG8_WAIT_L(n) asm volatile("s_waitcnt lgkmcnt(" #n ")" ::: "memory")
; #define PG8_BAR __builtin_amdgcn_s_barrier()
; #define PG8_SCHED __builtin_amdgcn_sched_barrier(0)
; template <class Epi, class Sched, bool ALIGN_EPI = false, bool SP2 = false>
; __device__ __forceinline__ void gemm_phase(LAS unsigned char* lds, const Gemm g, const Sched& S, const Epi& E) {
;     ...
;             PG8_WAIT_V(8); PG8_WAIT_L(0); PG8_BAR; PG8_MMA(0, 0, At, B0); PG8_MMA(0, 1, At, B1); PG8_BAR; PG8_SCHED;
;             PG8_LDA(At, 1, 1); PG8_STAGE(PG8_SB(1, 0), b3, voffB); PG8_STAGE(PG8_SB(1, 1), b3 + hstep, voffB); PG8_STAGE(PG8_SA(1, 0), a3, voffA);
;             PG8_WAIT_V(8); PG8_WAIT_L(0); PG8_BAR; PG8_MMA(1, 0, At, B0); PG8_MMA(1, 1, At, B1); PG8_BAR; PG8_SCHED;
;     ...
;         if constexpr (ALIGN_EPI) { if (wr == 0) PG8_BAR; }
	s_setprio 1
	s_waitcnt lgkmcnt(0)
	v_mfma_f32_16x16x32_bf16 v[124:127], v[128:131], v[182:185], v[124:127]
	v_mfma_f32_16x16x32_bf16 v[120:123], v[136:139], v[182:185], v[120:123]
	v_mfma_f32_16x16x32_bf16 v[108:111], v[128:131], v[190:193], v[108:111]
	v_mfma_f32_16x16x32_bf16 v[104:107], v[136:139], v[190:193], v[104:107]
	v_mfma_f32_16x16x32_bf16 v[92:95], v[128:131], v[198:201], v[92:95]
	v_mfma_f32_16x16x32_bf16 v[88:91], v[136:139], v[198:201], v[88:91]
	v_mfma_f32_16x16x32_bf16 v[76:79], v[128:131], v[222:225], v[76:79]
	v_mfma_f32_16x16x32_bf16 v[72:75], v[136:139], v[222:225], v[72:75]
	v_mfma_f32_16x16x32_bf16 v[124:127], v[132:135], v[186:189], v[124:127]
	v_mfma_f32_16x16x32_bf16 v[120:123], v[140:143], v[186:189], v[120:123]
	v_mfma_f32_16x16x32_bf16 v[108:111], v[132:135], v[194:197], v[108:111]
	v_mfma_f32_16x16x32_bf16 v[104:107], v[140:143], v[194:197], v[104:107]
	v_mfma_f32_16x16x32_bf16 v[92:95], v[132:135], v[202:205], v[92:95]
	v_mfma_f32_16x16x32_bf16 v[88:91], v[140:143], v[202:205], v[88:91]
	v_mfma_f32_16x16x32_bf16 v[76:79], v[132:135], v[226:229], v[76:79]
	v_mfma_f32_16x16x32_bf16 v[72:75], v[140:143], v[226:229], v[72:75]
	v_mfma_f32_16x16x32_bf16 v[116:119], v[166:169], v[182:185], v[116:119]
	v_mfma_f32_16x16x32_bf16 v[112:115], v[174:177], v[182:185], v[112:115]
	v_mfma_f32_16x16x32_bf16 v[100:103], v[166:169], v[190:193], v[100:103]
	v_mfma_f32_16x16x32_bf16 v[96:99], v[174:177], v[190:193], v[96:99]
	v_mfma_f32_16x16x32_bf16 v[84:87], v[166:169], v[198:201], v[84:87]
	v_mfma_f32_16x16x32_bf16 v[80:83], v[174:177], v[198:201], v[80:83]
	v_mfma_f32_16x16x32_bf16 v[68:71], v[166:169], v[222:225], v[68:71]
	v_mfma_f32_16x16x32_bf16 v[64:67], v[174:177], v[222:225], v[64:67]
	v_mfma_f32_16x16x32_bf16 v[116:119], v[170:173], v[186:189], v[116:119]
	v_mfma_f32_16x16x32_bf16 v[112:115], v[178:181], v[186:189], v[112:115]
	v_mfma_f32_16x16x32_bf16 v[100:103], v[170:173], v[194:197], v[100:103]
	v_mfma_f32_16x16x32_bf16 v[96:99], v[178:181], v[194:197], v[96:99]
	v_mfma_f32_16x16x32_bf16 v[84:87], v[170:173], v[202:205], v[84:87]
	v_mfma_f32_16x16x32_bf16 v[80:83], v[178:181], v[202:205], v[80:83]
	v_mfma_f32_16x16x32_bf16 v[68:71], v[170:173], v[226:229], v[68:71]
	v_mfma_f32_16x16x32_bf16 v[64:67], v[178:181], v[226:229], v[64:67]
	s_setprio 0
	s_barrier
	s_add_i32 s13, s13, s70
	v_lshl_add_u64 v[230:231], v[230:231], 0, s[30:31]
	s_mov_b32 m0, s13
	ds_read_b128 v[182:185], v221 offset:49152
	ds_read_b128 v[186:189], v221 offset:50176
	ds_read_b128 v[190:193], v221 offset:51200
	ds_read_b128 v[194:197], v221 offset:52224
	ds_read_b128 v[198:201], v221 offset:53248
	ds_read_b128 v[202:205], v221 offset:54272
	ds_read_b128 v[222:225], v221 offset:55296
	ds_read_b128 v[226:229], v221 offset:56320
	global_load_lds_dwordx4 v[230:231], off
	s_add_i32 m0, s13, 0x2000
	s_add_u32 s14, s36, 0x40080
	v_lshl_add_u64 v[230:231], v[232:233], 0, s[30:31]
	s_addc_u32 s15, s37, 0
	s_add_i32 s13, s16, s70
	global_load_lds_dwordx4 v[230:231], off
	s_waitcnt vmcnt(4)
	s_waitcnt lgkmcnt(0)
	s_barrier
	s_setprio 1
	s_waitcnt lgkmcnt(0)
	v_mfma_f32_16x16x32_bf16 v[60:63], v[128:131], v[182:185], v[60:63]
	v_mfma_f32_16x16x32_bf16 v[56:59], v[136:139], v[182:185], v[56:59]
	v_mfma_f32_16x16x32_bf16 v[44:47], v[128:131], v[190:193], v[44:47]
	v_lshl_add_u64 v[230:231], s[14:15], 0, v[148:149]
	s_mov_b32 m0, s13
	v_mfma_f32_16x16x32_bf16 v[40:43], v[136:139], v[190:193], v[40:43]
	global_load_lds_dwordx4 v[230:231], off
	v_mfma_f32_16x16x32_bf16 v[28:31], v[128:131], v[198:201], v[28:31]
	v_mfma_f32_16x16x32_bf16 v[24:27], v[136:139], v[198:201], v[24:27]
	v_mfma_f32_16x16x32_bf16 v[12:15], v[128:131], v[222:225], v[12:15]
	v_mfma_f32_16x16x32_bf16 v[8:11], v[136:139], v[222:225], v[8:11]
	v_mfma_f32_16x16x32_bf16 v[60:63], v[132:135], v[186:189], v[60:63]
	v_mfma_f32_16x16x32_bf16 v[56:59], v[140:143], v[186:189], v[56:59]
	v_lshl_add_u64 v[230:231], s[14:15], 0, v[144:145]
	s_add_i32 m0, s13, 0x2000
	v_mfma_f32_16x16x32_bf16 v[44:47], v[132:135], v[194:197], v[44:47]
	global_load_lds_dwordx4 v[230:231], off
	v_mfma_f32_16x16x32_bf16 v[40:43], v[140:143], v[194:197], v[40:43]
	v_mfma_f32_16x16x32_bf16 v[28:31], v[132:135], v[202:205], v[28:31]
	v_mfma_f32_16x16x32_bf16 v[24:27], v[140:143], v[202:205], v[24:27]
	v_mfma_f32_16x16x32_bf16 v[12:15], v[132:135], v[226:229], v[12:15]
	v_mfma_f32_16x16x32_bf16 v[8:11], v[140:143], v[226:229], v[8:11]
	v_mfma_f32_16x16x32_bf16 v[52:55], v[166:169], v[182:185], v[52:55]
	v_mfma_f32_16x16x32_bf16 v[48:51], v[174:177], v[182:185], v[48:51]
	v_lshl_add_u64 v[230:231], v[234:235], 0, s[30:31]
	s_mov_b32 m0, s96
	v_mfma_f32_16x16x32_bf16 v[36:39], v[166:169], v[190:193], v[36:39]
	global_load_lds_dwordx4 v[230:231], off
	v_mfma_f32_16x16x32_bf16 v[32:35], v[174:177], v[190:193], v[32:35]
	v_mfma_f32_16x16x32_bf16 v[20:23], v[166:169], v[198:201], v[20:23]
	v_mfma_f32_16x16x32_bf16 v[16:19], v[174:177], v[198:201], v[16:19]
	v_mfma_f32_16x16x32_bf16 v[4:7], v[166:169], v[222:225], v[4:7]
	v_mfma_f32_16x16x32_bf16 v[0:3], v[174:177], v[222:225], v[0:3]
	v_mfma_f32_16x16x32_bf16 v[52:55], v[170:173], v[186:189], v[52:55]
	v_mfma_f32_16x16x32_bf16 v[48:51], v[178:181], v[186:189], v[48:51]
	v_lshl_add_u64 v[230:231], v[236:237], 0, s[30:31]
	s_mov_b32 m0, s97
	v_mfma_f32_16x16x32_bf16 v[36:39], v[170:173], v[194:197], v[36:39]
	global_load_lds_dwordx4 v[230:231], off
	v_mfma_f32_16x16x32_bf16 v[32:35], v[178:181], v[194:197], v[32:35]
	v_mfma_f32_16x16x32_bf16 v[20:23], v[170:173], v[202:205], v[20:23]
	v_mfma_f32_16x16x32_bf16 v[16:19], v[178:181], v[202:205], v[16:19]
	v_mfma_f32_16x16x32_bf16 v[4:7], v[170:173], v[226:229], v[4:7]
	v_mfma_f32_16x16x32_bf16 v[0:3], v[178:181], v[226:229], v[0:3]
	s_setprio 0
	s_barrier
	s_add_i32 s12, s12, 2
	s_add_u32 s24, s24, 0x100
	s_addc_u32 s25, s25, 0
	s_add_u32 s10, s10, 0x100
	s_addc_u32 s11, s11, 0
	s_cmp_gt_u32 s12, 13
	s_cbranch_scc0 .LBB0_418
	s_and_b64 vcc, exec, s[50:51]
	s_cbranch_vccz .LBB0_421
	s_barrier

; #define PG8_STAGE(bufoff, gbase, voff) do { _Pragma("unroll") for (int _i = 0; _i < 2; ++_i) \
;         __builtin_amdgcn_global_load_lds((const unsigned*)((const char*)(gbase) + (voff)[_i]), (LAS unsigned*)(lds + (bufoff) + ldsw + _i * 8192), 16, 0, 0); } while (0)
; #define PG8_LDA(dst, b, h) do { _Pragma("unroll") for (int m = 0; m < 4; ++m) _Pragma("unroll") for (int k = 0; k < 2; ++k) dst[m][k] = *(const LAS bf16x8*)(lds + PG8_SA(b, h) + aoff + m * 2048 + k * 1024); } while (0)
; #define PG8_LDB(dst, b, h) do { _Pragma("unroll") for (int n = 0; n < 2; ++n) _Pragma("unroll") for (int k = 0; k < 2; ++k) dst[n][k] = *(const LAS bf16x8*)(lds + PG8_SB(b, h) + boff + n * 2048 + k * 1024); } while (0)
; #define PG8_WAIT_V(n) asm volatile("s_waitcnt vmcnt(" #n ")" ::: "memory")
; #define PG8_WAIT_L(n) asm volatile("s_waitcnt lgkmcnt(" #n ")" ::: "memory")
; #define PG8_BAR __builtin_amdgcn_s_barrier()
; #define PG8_SCHED __builtin_amdgcn_sched_barrier(0)
; template <class Epi, class Sched, bool ALIGN_EPI = false, bool SP2 = false>
; __device__ __forceinline__ void gemm_phase(LAS unsigned char* lds, const Gemm g, const Sched& S, const Epi& E) {
;     ...
;         const bool has_next = S.next(ui + 1, nxt);
;         const char* nA = has_next ? (const char*)g.A + (size_t)nxt.pm * tstep : cA; const char* nB = has_next ? (const char*)g.Bt + (size_t)nxt.pn * tstep : cB;
;         for (int t = 0; t < nt; t += 2) {
;             const bool last = (t == nt - 2);
;             const char* a1 = cA + (size_t)(t + 1) * kstep;
;             const char* a2 = last ? nA : cA + (size_t)(t + 2) * kstep; const char* b2 = last ? nB : cB + (size_t)(t + 2) * kstep;
;             const char* a3 = a2 + kstep; const char* b3 = b2 + kstep;
;             if (last && has_next) S.a_ready(nxt);
;             if constexpr (SP2) {
;             PG8_LDB(B0, 0, 0); PG8_LDB(B1, 0, 1); PG8_SCHED; PG8_LDA(At, 0, 0); PG8_STAGE(PG8_SA(1, 1), a1 + hstep, voffA);
;             PG8_WAIT_V(8); PG8_WAIT_L(0); PG8_BAR; PG8_MMA(0, 0, At, B0); PG8_MMA(0, 1, At, B1); PG8_BAR; PG8_SCHED;
;             PG8_LDA(At, 0, 1); PG8_STAGE(PG8_SB(0, 0), b2, voffB); PG8_STAGE(PG8_SB(0, 1), b2 + hstep, voffB); PG8_STAGE(PG8_SA(0, 0), a2, voffA);
;             PG8_WAIT_V(8); PG8_WAIT_L(0); PG8_BAR; PG8_MMA(1, 0, At, B0); PG8_MMA(1, 1, At, B1); PG8_BAR; PG8_SCHED;
.LBB0_534:
	s_add_u32 s14, s46, 0xfffc0080
	s_addc_u32 s15, s47, -1
	s_add_i32 s16, 0, 0x10000
	s_cmp_eq_u32 s82, 12
	s_cselect_b32 s55, s39, s15
	s_cselect_b32 s54, s71, s14
	s_cselect_b32 s51, s37, s79
	s_cselect_b32 s50, s72, s73
	s_add_i32 s17, 0, 0x14000
	v_add_u32_e32 v140, s16, v194
	v_add_u32_e32 v180, s17, v194
	ds_read_b128 v[128:131], v140
	ds_read_b128 v[132:135], v140 offset:1024
	ds_read_b128 v[136:139], v140 offset:2048
	ds_read_b128 v[140:143], v140 offset:3072
	ds_read_b128 v[144:147], v180
	ds_read_b128 v[148:151], v180 offset:1024
	ds_read_b128 v[176:179], v180 offset:2048
	ds_read_b128 v[180:183], v180 offset:3072
	v_lshl_add_u64 v[234:235], s[46:47], 0, v[172:173]
	s_add_i32 m0, s7, 0xc000
	ds_read_b128 v[184:187], v196
	ds_read_b128 v[190:193], v196 offset:1024
	ds_read_b128 v[198:201], v196 offset:2048
	ds_read_b128 v[202:205], v196 offset:3072
	ds_read_b128 v[218:221], v196 offset:4096
	ds_read_b128 v[222:225], v196 offset:5120
	ds_read_b128 v[226:229], v196 offset:6144
	ds_read_b128 v[230:233], v196 offset:7168
	global_load_lds_dwordx4 v[234:235], off
	v_lshl_add_u64 v[234:235], s[46:47], 0, v[174:175]
	s_add_i32 m0, s7, 0xe000
	s_nop 0
	global_load_lds_dwordx4 v[234:235], off
	s_waitcnt vmcnt(8)
	s_waitcnt lgkmcnt(0)
	s_barrier
	s_setprio 1
	s_waitcnt lgkmcnt(0)
	v_mfma_f32_16x16x32_bf16 v[124:127], v[128:131], v[184:187], v[124:127]
	v_mfma_f32_16x16x32_bf16 v[120:123], v[136:139], v[184:187], v[120:123]
	v_mfma_f32_16x16x32_bf16 v[108:111], v[128:131], v[198:201], v[108:111]
	v_mfma_f32_16x16x32_bf16 v[104:107], v[136:139], v[198:201], v[104:107]
	v_mfma_f32_16x16x32_bf16 v[92:95], v[128:131], v[218:221], v[92:95]
	v_mfma_f32_16x16x32_bf16 v[88:91], v[136:139], v[218:221], v[88:91]
	v_mfma_f32_16x16x32_bf16 v[76:79], v[128:131], v[226:229], v[76:79]
	v_mfma_f32_16x16x32_bf16 v[72:75], v[136:139], v[226:229], v[72:75]
	v_mfma_f32_16x16x32_bf16 v[124:127], v[132:135], v[190:193], v[124:127]
	v_mfma_f32_16x16x32_bf16 v[120:123], v[140:143], v[190:193], v[120:123]
	v_mfma_f32_16x16x32_bf16 v[108:111], v[132:135], v[202:205], v[108:111]
	v_mfma_f32_16x16x32_bf16 v[104:107], v[140:143], v[202:205], v[104:107]
	v_mfma_f32_16x16x32_bf16 v[92:95], v[132:135], v[222:225], v[92:95]
	v_mfma_f32_16x16x32_bf16 v[88:91], v[140:143], v[222:225], v[88:91]
	v_mfma_f32_16x16x32_bf16 v[76:79], v[132:135], v[230:233], v[76:79]
	v_mfma_f32_16x16x32_bf16 v[72:75], v[140:143], v[230:233], v[72:75]
	v_mfma_f32_16x16x32_bf16 v[116:119], v[144:147], v[184:187], v[116:119]
	v_mfma_f32_16x16x32_bf16 v[112:115], v[176:179], v[184:187], v[112:115]
	v_mfma_f32_16x16x32_bf16 v[100:103], v[144:147], v[198:201], v[100:103]
	v_mfma_f32_16x16x32_bf16 v[96:99], v[176:179], v[198:201], v[96:99]
	v_mfma_f32_16x16x32_bf16 v[84:87], v[144:147], v[218:221], v[84:87]
	v_mfma_f32_16x16x32_bf16 v[80:83], v[176:179], v[218:221], v[80:83]
	v_mfma_f32_16x16x32_bf16 v[68:71], v[144:147], v[226:229], v[68:71]
	v_mfma_f32_16x16x32_bf16 v[64:67], v[176:179], v[226:229], v[64:67]
	v_mfma_f32_16x16x32_bf16 v[116:119], v[148:151], v[190:193], v[116:119]
	v_mfma_f32_16x16x32_bf16 v[112:115], v[180:183], v[190:193], v[112:115]
	v_mfma_f32_16x16x32_bf16 v[100:103], v[148:151], v[202:205], v[100:103]
	v_mfma_f32_16x16x32_bf16 v[96:99], v[180:183], v[202:205], v[96:99]
	v_mfma_f32_16x16x32_bf16 v[84:87], v[148:151], v[222:225], v[84:87]
	v_mfma_f32_16x16x32_bf16 v[80:83], v[180:183], v[222:225], v[80:83]
	v_mfma_f32_16x16x32_bf16 v[68:71], v[148:151], v[230:233], v[68:71]
	v_mfma_f32_16x16x32_bf16 v[64:67], v[180:183], v[230:233], v[64:67]
	s_setprio 0
	s_barrier
	s_add_i32 s14, s16, s6
	v_lshl_add_u64 v[234:235], s[50:51], 0, v[166:167]
	s_mov_b32 m0, s14
	ds_read_b128 v[184:187], v196 offset:16384
	ds_read_b128 v[190:193], v196 offset:17408
	ds_read_b128 v[198:201], v196 offset:18432
	ds_read_b128 v[202:205], v196 offset:19456
	ds_read_b128 v[218:221], v196 offset:20480
	ds_read_b128 v[222:225], v196 offset:21504
	ds_read_b128 v[226:229], v196 offset:22528
	ds_read_b128 v[230:233], v196 offset:23552
	global_load_lds_dwordx4 v[234:235], off
	s_add_i32 m0, s14, 0x2000
	s_add_u32 s14, s50, 0x40000
	v_lshl_add_u64 v[236:237], s[50:51], 0, v[162:163]
	s_addc_u32 s15, s51, 0
	s_add_i32 s16, s17, s6
	global_load_lds_dwordx4 v[236:237], off
	s_waitcnt vmcnt(4)
	s_waitcnt lgkmcnt(0)
	s_barrier
; #define PG8_STAGE(bufoff, gbase, voff) do { _Pragma("unroll") for (int _i = 0; _i < 2; ++_i) \
;         __builtin_amdgcn_global_load_lds((const unsigned*)((const char*)(gbase) + (voff)[_i]), (LAS unsigned*)(lds + (bufoff) + ldsw + _i * 8192), 16, 0, 0); } while (0)
; #define PG8_LDA(dst, b, h) do { _Pragma("unroll") for (int m = 0; m < 4; ++m) _Pragma("unroll") for (int k = 0; k < 2; ++k) dst[m][k] = *(const LAS bf16x8*)(lds + PG8_SA(b, h) + aoff + m * 2048 + k * 1024); } while (0)
; #define PG8_LDB(dst, b, h) do { _Pragma("unroll") for (int n = 0; n < 2; ++n) _Pragma("unroll") for (int k = 0; k < 2; ++k) dst[n][k] = *(const LAS bf16x8*)(lds + PG8_SB(b, h) + boff + n * 2048 + k * 1024); } while (0)
; #define PG8_MMA(ai, bj, At, Bt) do { __builtin_amdgcn_s_setprio(1); _Pragma("unroll") for (int m = 0; m < 4; ++m) _Pragma("unroll") for (int n = 0; n < 2; ++n) _Pragma("unroll") for (int k = 0; k < 2; ++k) \
;         acc[ai][bj][m][n] = __builtin_amdgcn_mfma_f32_16x16x32_bf16(Bt[n][k], At[m][k], acc[ai][bj][m][n], 0, 0, 0); __builtin_amdgcn_s_setprio(0); } while (0)
; #define PG8_WAIT_V(n) asm volatile("s_waitcnt vmcnt(" #n ")" ::: "memory")
; #define PG8_WAIT_L(n) asm volatile("s_waitcnt lgkmcnt(" #n ")" ::: "memory")
; #define PG8_BAR __builtin_amdgcn_s_barrier()
; #define PG8_SCHED __builtin_amdgcn_sched_barrier(0)
; template <class Epi, class Sched, bool ALIGN_EPI = false, bool SP2 = false>
; __device__ __forceinline__ void gemm_phase(LAS unsigned char* lds, const Gemm g, const Sched& S, const Epi& E) {
;     ...
;             PG8_WAIT_V(8); PG8_WAIT_L(0); PG8_BAR; PG8_MMA(1, 0, At, B0); PG8_MMA(1, 1, At, B1); PG8_BAR; PG8_SCHED;
;             PG8_LDB(B0, 1, 0); PG8_LDB(B1, 1, 1); PG8_SCHED; PG8_LDA(At, 1, 0); PG8_STAGE(PG8_SA(0, 1), a2 + hstep, voffA);
;             PG8_WAIT_V(8); PG8_WAIT_L(0); PG8_BAR; PG8_MMA(0, 0, At, B0); PG8_MMA(0, 1, At, B1); PG8_BAR; PG8_SCHED;
	s_setprio 1
	s_waitcnt lgkmcnt(0)
	v_mfma_f32_16x16x32_bf16 v[60:63], v[128:131], v[184:187], v[60:63]
	v_mfma_f32_16x16x32_bf16 v[56:59], v[136:139], v[184:187], v[56:59]
	v_mfma_f32_16x16x32_bf16 v[44:47], v[128:131], v[198:201], v[44:47]
	v_lshl_add_u64 v[238:239], s[14:15], 0, v[166:167]
	s_mov_b32 m0, s16
	v_lshl_add_u64 v[240:241], s[54:55], 0, v[164:165]
	v_mfma_f32_16x16x32_bf16 v[40:43], v[136:139], v[198:201], v[40:43]
	global_load_lds_dwordx4 v[238:239], off
	v_mfma_f32_16x16x32_bf16 v[28:31], v[128:131], v[218:221], v[28:31]
	v_mfma_f32_16x16x32_bf16 v[24:27], v[136:139], v[218:221], v[24:27]
	v_mfma_f32_16x16x32_bf16 v[12:15], v[128:131], v[226:229], v[12:15]
	v_mfma_f32_16x16x32_bf16 v[8:11], v[136:139], v[226:229], v[8:11]
	v_mfma_f32_16x16x32_bf16 v[60:63], v[132:135], v[190:193], v[60:63]
	v_mfma_f32_16x16x32_bf16 v[56:59], v[140:143], v[190:193], v[56:59]
	v_lshl_add_u64 v[238:239], s[14:15], 0, v[162:163]
	s_add_i32 m0, s16, 0x2000
	v_mfma_f32_16x16x32_bf16 v[44:47], v[132:135], v[202:205], v[44:47]
	global_load_lds_dwordx4 v[238:239], off
	v_mfma_f32_16x16x32_bf16 v[40:43], v[140:143], v[202:205], v[40:43]
	v_mfma_f32_16x16x32_bf16 v[28:31], v[132:135], v[222:225], v[28:31]
	v_mfma_f32_16x16x32_bf16 v[24:27], v[140:143], v[222:225], v[24:27]
	v_mfma_f32_16x16x32_bf16 v[12:15], v[132:135], v[230:233], v[12:15]
	v_mfma_f32_16x16x32_bf16 v[8:11], v[140:143], v[230:233], v[8:11]
	v_mfma_f32_16x16x32_bf16 v[52:55], v[144:147], v[184:187], v[52:55]
	v_mfma_f32_16x16x32_bf16 v[48:51], v[176:179], v[184:187], v[48:51]
	v_lshl_add_u64 v[238:239], s[54:55], 0, v[168:169]
	s_mov_b32 m0, s7
	v_mfma_f32_16x16x32_bf16 v[36:39], v[144:147], v[198:201], v[36:39]
	global_load_lds_dwordx4 v[238:239], off
	v_mfma_f32_16x16x32_bf16 v[32:35], v[176:179], v[198:201], v[32:35]
	v_mfma_f32_16x16x32_bf16 v[20:23], v[144:147], v[218:221], v[20:23]
	v_mfma_f32_16x16x32_bf16 v[16:19], v[176:179], v[218:221], v[16:19]
	v_mfma_f32_16x16x32_bf16 v[4:7], v[144:147], v[226:229], v[4:7]
	v_mfma_f32_16x16x32_bf16 v[0:3], v[176:179], v[226:229], v[0:3]
	v_mfma_f32_16x16x32_bf16 v[52:55], v[148:151], v[190:193], v[52:55]
	v_mfma_f32_16x16x32_bf16 v[48:51], v[180:183], v[190:193], v[48:51]
	s_mov_b32 m0, s8
	v_mfma_f32_16x16x32_bf16 v[36:39], v[148:151], v[202:205], v[36:39]
	global_load_lds_dwordx4 v[240:241], off
	v_mfma_f32_16x16x32_bf16 v[32:35], v[180:183], v[202:205], v[32:35]
	v_mfma_f32_16x16x32_bf16 v[20:23], v[148:151], v[222:225], v[20:23]
	v_mfma_f32_16x16x32_bf16 v[16:19], v[180:183], v[222:225], v[16:19]
	v_mfma_f32_16x16x32_bf16 v[4:7], v[148:151], v[230:233], v[4:7]
	v_mfma_f32_16x16x32_bf16 v[0:3], v[180:183], v[230:233], v[0:3]
	s_setprio 0
	s_barrier
	s_add_i32 s16, 0, 0x18000
	s_add_i32 s17, 0, 0x1c000
	v_add_u32_e32 v140, s16, v194
	v_add_u32_e32 v180, s17, v194
	ds_read_b128 v[128:131], v140
	ds_read_b128 v[132:135], v140 offset:1024
	ds_read_b128 v[136:139], v140 offset:2048
	ds_read_b128 v[140:143], v140 offset:3072
	ds_read_b128 v[144:147], v180
	ds_read_b128 v[148:151], v180 offset:1024
	ds_read_b128 v[176:179], v180 offset:2048
	ds_read_b128 v[180:183], v180 offset:3072
	s_add_u32 s14, s54, 0x40000
	s_addc_u32 s15, s55, 0
	s_mov_b32 m0, s9
	v_lshl_add_u64 v[242:243], s[14:15], 0, v[168:169]
	ds_read_b128 v[184:187], v196 offset:32768
	ds_read_b128 v[190:193], v196 offset:33792
	ds_read_b128 v[198:201], v196 offset:34816
	ds_read_b128 v[202:205], v196 offset:35840
	ds_read_b128 v[218:221], v196 offset:36864
	ds_read_b128 v[222:225], v196 offset:37888
	ds_read_b128 v[226:229], v196 offset:38912
	ds_read_b128 v[230:233], v196 offset:39936
	global_load_lds_dwordx4 v[242:243], off
	v_lshl_add_u64 v[242:243], s[14:15], 0, v[164:165]
	s_mov_b32 m0, s10
	s_nop 0
	global_load_lds_dwordx4 v[242:243], off
	s_waitcnt vmcnt(8)
	s_waitcnt lgkmcnt(0)
	s_barrier
; #define PG8_STAGE(bufoff, gbase, voff) do { _Pragma("unroll") for (int _i = 0; _i < 2; ++_i) \
;         __builtin_amdgcn_global_load_lds((const unsigned*)((const char*)(gbase) + (voff)[_i]), (LAS unsigned*)(lds + (bufoff) + ldsw + _i * 8192), 16, 0, 0); } while (0)
; #define PG8_LDA(dst, b, h) do { _Pragma("unroll") for (int m = 0; m < 4; ++m) _Pragma("unroll") for (int k = 0; k < 2; ++k) dst[m][k] = *(const LAS bf16x8*)(lds + PG8_SA(b, h) + aoff + m * 2048 + k * 1024); } while (0)
; #define PG8_MMA(ai, bj, At, Bt) do { __builtin_amdgcn_s_setprio(1); _Pragma("unroll") for (int m = 0; m < 4; ++m) _Pragma("unroll") for (int n = 0; n < 2; ++n) _Pragma("unroll") for (int k = 0; k < 2; ++k) \
;         acc[ai][bj][m][n] = __builtin_amdgcn_mfma_f32_16x16x32_bf16(Bt[n][k], At[m][k], acc[ai][bj][m][n], 0, 0, 0); __builtin_amdgcn_s_setprio(0); } while (0)
; #define PG8_WAIT_V(n) asm volatile("s_waitcnt vmcnt(" #n ")" ::: "memory")
; #define PG8_WAIT_L(n) asm volatile("s_waitcnt lgkmcnt(" #n ")" ::: "memory")
; #define PG8_BAR __builtin_amdgcn_s_barrier()
; #define PG8_SCHED __builtin_amdgcn_sched_barrier(0)
; template <class Epi, class Sched, bool ALIGN_EPI = false, bool SP2 = false>
; __device__ __forceinline__ void gemm_phase(LAS unsigned char* lds, const Gemm g, const Sched& S, const Epi& E) {
;     ...
;             PG8_WAIT_V(8); PG8_WAIT_L(0); PG8_BAR; PG8_MMA(0, 0, At, B0); PG8_MMA(0, 1, At, B1); PG8_BAR; PG8_SCHED;
;             PG8_LDA(At, 1, 1); PG8_STAGE(PG8_SB(1, 0), b3, voffB); PG8_STAGE(PG8_SB(1, 1), b3 + hstep, voffB); PG8_STAGE(PG8_SA(1, 0), a3, voffA);
;             PG8_WAIT_V(8); PG8_WAIT_L(0); PG8_BAR; PG8_MMA(1, 0, At, B0); PG8_MMA(1, 1, At, B1); PG8_BAR; PG8_SCHED;
;     ...
;         if constexpr (ALIGN_EPI) { if (wr == 0) PG8_BAR; }
	s_setprio 1
	s_waitcnt lgkmcnt(0)
	v_mfma_f32_16x16x32_bf16 v[124:127], v[128:131], v[184:187], v[124:127]
	v_mfma_f32_16x16x32_bf16 v[120:123], v[136:139], v[184:187], v[120:123]
	v_mfma_f32_16x16x32_bf16 v[108:111], v[128:131], v[198:201], v[108:111]
	v_mfma_f32_16x16x32_bf16 v[104:107], v[136:139], v[198:201], v[104:107]
	v_mfma_f32_16x16x32_bf16 v[92:95], v[128:131], v[218:221], v[92:95]
	v_mfma_f32_16x16x32_bf16 v[88:91], v[136:139], v[218:221], v[88:91]
	v_mfma_f32_16x16x32_bf16 v[76:79], v[128:131], v[226:229], v[76:79]
	v_mfma_f32_16x16x32_bf16 v[72:75], v[136:139], v[226:229], v[72:75]
	v_mfma_f32_16x16x32_bf16 v[124:127], v[132:135], v[190:193], v[124:127]
	v_mfma_f32_16x16x32_bf16 v[120:123], v[140:143], v[190:193], v[120:123]
	v_mfma_f32_16x16x32_bf16 v[108:111], v[132:135], v[202:205], v[108:111]
	v_mfma_f32_16x16x32_bf16 v[104:107], v[140:143], v[202:205], v[104:107]
	v_mfma_f32_16x16x32_bf16 v[92:95], v[132:135], v[222:225], v[92:95]
	v_mfma_f32_16x16x32_bf16 v[88:91], v[140:143], v[222:225], v[88:91]
	v_mfma_f32_16x16x32_bf16 v[76:79], v[132:135], v[230:233], v[76:79]
	v_mfma_f32_16x16x32_bf16 v[72:75], v[140:143], v[230:233], v[72:75]
	v_mfma_f32_16x16x32_bf16 v[116:119], v[144:147], v[184:187], v[116:119]
	v_mfma_f32_16x16x32_bf16 v[112:115], v[176:179], v[184:187], v[112:115]
	v_mfma_f32_16x16x32_bf16 v[100:103], v[144:147], v[198:201], v[100:103]
	v_mfma_f32_16x16x32_bf16 v[96:99], v[176:179], v[198:201], v[96:99]
	v_mfma_f32_16x16x32_bf16 v[84:87], v[144:147], v[218:221], v[84:87]
	v_mfma_f32_16x16x32_bf16 v[80:83], v[176:179], v[218:221], v[80:83]
	v_mfma_f32_16x16x32_bf16 v[68:71], v[144:147], v[226:229], v[68:71]
	v_mfma_f32_16x16x32_bf16 v[64:67], v[176:179], v[226:229], v[64:67]
	v_mfma_f32_16x16x32_bf16 v[116:119], v[148:151], v[190:193], v[116:119]
	v_mfma_f32_16x16x32_bf16 v[112:115], v[180:183], v[190:193], v[112:115]
	v_mfma_f32_16x16x32_bf16 v[100:103], v[148:151], v[202:205], v[100:103]
	v_mfma_f32_16x16x32_bf16 v[96:99], v[180:183], v[202:205], v[96:99]
	v_mfma_f32_16x16x32_bf16 v[84:87], v[148:151], v[222:225], v[84:87]
	v_mfma_f32_16x16x32_bf16 v[80:83], v[180:183], v[222:225], v[80:83]
	v_mfma_f32_16x16x32_bf16 v[68:71], v[148:151], v[230:233], v[68:71]
	v_mfma_f32_16x16x32_bf16 v[64:67], v[180:183], v[230:233], v[64:67]
	s_setprio 0
	s_barrier
	s_add_i32 s14, s16, s6
	v_lshl_add_u64 v[234:235], v[234:235], 0, s[30:31]
	s_mov_b32 m0, s14
	ds_read_b128 v[184:187], v196 offset:49152
	ds_read_b128 v[190:193], v196 offset:50176
	ds_read_b128 v[198:201], v196 offset:51200
	ds_read_b128 v[202:205], v196 offset:52224
	ds_read_b128 v[218:221], v196 offset:53248
	ds_read_b128 v[222:225], v196 offset:54272
	ds_read_b128 v[226:229], v196 offset:55296
	ds_read_b128 v[230:233], v196 offset:56320
	global_load_lds_dwordx4 v[234:235], off
	s_add_i32 m0, s14, 0x2000
	s_add_u32 s14, s50, 0x40080
	v_lshl_add_u64 v[234:235], v[236:237], 0, s[30:31]
	s_addc_u32 s15, s51, 0
	s_add_i32 s16, s17, s6
	global_load_lds_dwordx4 v[234:235], off
	s_waitcnt vmcnt(4)
	s_waitcnt lgkmcnt(0)
	s_barrier
	s_setprio 1
	s_waitcnt lgkmcnt(0)
	v_mfma_f32_16x16x32_bf16 v[60:63], v[128:131], v[184:187], v[60:63]
	v_mfma_f32_16x16x32_bf16 v[56:59], v[136:139], v[184:187], v[56:59]
	v_mfma_f32_16x16x32_bf16 v[44:47], v[128:131], v[198:201], v[44:47]
	v_lshl_add_u64 v[234:235], s[14:15], 0, v[166:167]
	s_mov_b32 m0, s16
	v_mfma_f32_16x16x32_bf16 v[40:43], v[136:139], v[198:201], v[40:43]
	global_load_lds_dwordx4 v[234:235], off
	v_mfma_f32_16x16x32_bf16 v[28:31], v[128:131], v[218:221], v[28:31]
	v_mfma_f32_16x16x32_bf16 v[24:27], v[136:139], v[218:221], v[24:27]
	v_mfma_f32_16x16x32_bf16 v[12:15], v[128:131], v[226:229], v[12:15]
	v_mfma_f32_16x16x32_bf16 v[8:11], v[136:139], v[226:229], v[8:11]
	v_mfma_f32_16x16x32_bf16 v[60:63], v[132:135], v[190:193], v[60:63]
	v_mfma_f32_16x16x32_bf16 v[56:59], v[140:143], v[190:193], v[56:59]
	v_lshl_add_u64 v[234:235], s[14:15], 0, v[162:163]
	s_add_i32 m0, s16, 0x2000
	v_mfma_f32_16x16x32_bf16 v[44:47], v[132:135], v[202:205], v[44:47]
	global_load_lds_dwordx4 v[234:235], off
	v_mfma_f32_16x16x32_bf16 v[40:43], v[140:143], v[202:205], v[40:43]
	v_mfma_f32_16x16x32_bf16 v[28:31], v[132:135], v[222:225], v[28:31]
	v_mfma_f32_16x16x32_bf16 v[24:27], v[140:143], v[222:225], v[24:27]
	v_mfma_f32_16x16x32_bf16 v[12:15], v[132:135], v[230:233], v[12:15]
	v_mfma_f32_16x16x32_bf16 v[8:11], v[140:143], v[230:233], v[8:11]
	v_mfma_f32_16x16x32_bf16 v[52:55], v[144:147], v[184:187], v[52:55]
	v_mfma_f32_16x16x32_bf16 v[48:51], v[176:179], v[184:187], v[48:51]
	v_lshl_add_u64 v[234:235], v[238:239], 0, s[30:31]
	s_mov_b32 m0, s11
	v_mfma_f32_16x16x32_bf16 v[36:39], v[144:147], v[198:201], v[36:39]
	global_load_lds_dwordx4 v[234:235], off
	v_mfma_f32_16x16x32_bf16 v[32:35], v[176:179], v[198:201], v[32:35]
	v_mfma_f32_16x16x32_bf16 v[20:23], v[144:147], v[218:221], v[20:23]
	v_mfma_f32_16x16x32_bf16 v[16:19], v[176:179], v[218:221], v[16:19]
	v_mfma_f32_16x16x32_bf16 v[4:7], v[144:147], v[226:229], v[4:7]
	v_mfma_f32_16x16x32_bf16 v[0:3], v[176:179], v[226:229], v[0:3]
	v_mfma_f32_16x16x32_bf16 v[52:55], v[148:151], v[190:193], v[52:55]
	v_mfma_f32_16x16x32_bf16 v[48:51], v[180:183], v[190:193], v[48:51]
	v_lshl_add_u64 v[234:235], v[240:241], 0, s[30:31]
	s_mov_b32 m0, s12
	v_mfma_f32_16x16x32_bf16 v[36:39], v[148:151], v[202:205], v[36:39]
	global_load_lds_dwordx4 v[234:235], off
	v_mfma_f32_16x16x32_bf16 v[32:35], v[180:183], v[202:205], v[32:35]
	v_mfma_f32_16x16x32_bf16 v[20:23], v[148:151], v[222:225], v[20:23]
	v_mfma_f32_16x16x32_bf16 v[16:19], v[180:183], v[222:225], v[16:19]
	v_mfma_f32_16x16x32_bf16 v[4:7], v[148:151], v[230:233], v[4:7]
	v_mfma_f32_16x16x32_bf16 v[0:3], v[180:183], v[230:233], v[0:3]
	s_setprio 0
	s_barrier
	s_add_i32 s82, s82, 2
	s_add_u32 s46, s46, 0x100
	s_addc_u32 s47, s47, 0
	s_add_u32 s73, s73, 0x100
	s_addc_u32 s79, s79, 0
	s_cmp_gt_u32 s82, 13
	s_cbranch_scc0 .LBB0_534
	s_and_b64 vcc, exec, s[28:29]
	s_cbranch_vccz .LBB0_537
	s_barrier

; #define PG8_STAGE(bufoff, gbase, voff) do { _Pragma("unroll") for (int _i = 0; _i < 2; ++_i) \
;         __builtin_amdgcn_global_load_lds((const unsigned*)((const char*)(gbase) + (voff)[_i]), (LAS unsigned*)(lds + (bufoff) + ldsw + _i * 8192), 16, 0, 0); } while (0)
; #define PG8_LDA(dst, b, h) do { _Pragma("unroll") for (int m = 0; m < 4; ++m) _Pragma("unroll") for (int k = 0; k < 2; ++k) dst[m][k] = *(const LAS bf16x8*)(lds + PG8_SA(b, h) + aoff + m * 2048 + k * 1024); } while (0)
; #define PG8_LDB(dst, b, h) do { _Pragma("unroll") for (int n = 0; n < 2; ++n) _Pragma("unroll") for (int k = 0; k < 2; ++k) dst[n][k] = *(const LAS bf16x8*)(lds + PG8_SB(b, h) + boff + n * 2048 + k * 1024); } while (0)
; #define PG8_WAIT_V(n) asm volatile("s_waitcnt vmcnt(" #n ")" ::: "memory")
; #define PG8_WAIT_L(n) asm volatile("s_waitcnt lgkmcnt(" #n ")" ::: "memory")
; #define PG8_BAR __builtin_amdgcn_s_barrier()
; #define PG8_SCHED __builtin_amdgcn_sched_barrier(0)
; template <class Epi, class Sched, bool ALIGN_EPI = false, bool SP2 = false>
; __device__ __forceinline__ void gemm_phase(LAS unsigned char* lds, const Gemm g, const Sched& S, const Epi& E) {
;     ...
;         const bool has_next = S.next(ui + 1, nxt);
;         const char* nA = has_next ? (const char*)g.A + (size_t)nxt.pm * tstep : cA; const char* nB = has_next ? (const char*)g.Bt + (size_t)nxt.pn * tstep : cB;
;         for (int t = 0; t < nt; t += 2) {
;             const bool last = (t == nt - 2);
;             const char* a1 = cA + (size_t)(t + 1) * kstep;
;             const char* a2 = last ? nA : cA + (size_t)(t + 2) * kstep; const char* b2 = last ? nB : cB + (size_t)(t + 2) * kstep;
;             const char* a3 = a2 + kstep; const char* b3 = b2 + kstep;
;             if (last && has_next) S.a_ready(nxt);
;             if constexpr (SP2) {
;             PG8_LDB(B0, 0, 0); PG8_LDB(B1, 0, 1); PG8_SCHED; PG8_LDA(At, 0, 0); PG8_STAGE(PG8_SA(1, 1), a1 + hstep, voffA);
;             PG8_WAIT_V(8); PG8_WAIT_L(0); PG8_BAR; PG8_MMA(0, 0, At, B0); PG8_MMA(0, 1, At, B1); PG8_BAR; PG8_SCHED;
;             PG8_LDA(At, 0, 1); PG8_STAGE(PG8_SB(0, 0), b2, voffB); PG8_STAGE(PG8_SB(0, 1), b2 + hstep, voffB); PG8_STAGE(PG8_SA(0, 0), a2, voffA);
;             PG8_WAIT_V(8); PG8_WAIT_L(0); PG8_BAR; PG8_MMA(1, 0, At, B0); PG8_MMA(1, 1, At, B1); PG8_BAR; PG8_SCHED;
.LBB0_612:
	s_add_u32 s14, s42, 0xfff00080
	s_addc_u32 s15, s43, -1
	s_add_i32 s16, 0, 0x10000
	s_cmp_eq_u32 s71, 60
	s_cselect_b32 s49, s37, s15
	s_cselect_b32 s48, s54, s14
	s_cselect_b32 s47, s29, s65
	s_cselect_b32 s46, s55, s64
	s_add_i32 s17, 0, 0x14000
	v_add_u32_e32 v140, s16, v175
	v_add_u32_e32 v172, s17, v175
	ds_read_b128 v[128:131], v140
	ds_read_b128 v[132:135], v140 offset:1024
	ds_read_b128 v[136:139], v140 offset:2048
	ds_read_b128 v[140:143], v140 offset:3072
	ds_read_b128 v[164:167], v172
	ds_read_b128 v[168:171], v172 offset:1024
	ds_read_b128 v[180:183], v172 offset:2048
	ds_read_b128 v[184:187], v172 offset:3072
	v_lshl_add_u64 v[172:173], s[42:43], 0, v[150:151]
	s_add_i32 m0, s7, 0xc000
	ds_read_b128 v[188:191], v178
	ds_read_b128 v[192:195], v178 offset:1024
	ds_read_b128 v[196:199], v178 offset:2048
	ds_read_b128 v[200:203], v178 offset:3072
	ds_read_b128 v[218:221], v178 offset:4096
	ds_read_b128 v[222:225], v178 offset:5120
	ds_read_b128 v[226:229], v178 offset:6144
	ds_read_b128 v[230:233], v178 offset:7168
	global_load_lds_dwordx4 v[172:173], off
	v_lshl_add_u64 v[172:173], s[42:43], 0, v[162:163]
	s_add_i32 m0, s7, 0xe000
	s_nop 0
	global_load_lds_dwordx4 v[172:173], off
	s_waitcnt vmcnt(8)
	s_waitcnt lgkmcnt(0)
	s_barrier
	s_setprio 1
	s_waitcnt lgkmcnt(0)
	v_mfma_f32_16x16x32_bf16 v[124:127], v[128:131], v[188:191], v[124:127]
	v_mfma_f32_16x16x32_bf16 v[120:123], v[136:139], v[188:191], v[120:123]
	v_mfma_f32_16x16x32_bf16 v[112:115], v[128:131], v[196:199], v[112:115]
	v_mfma_f32_16x16x32_bf16 v[104:107], v[136:139], v[196:199], v[104:107]
	v_mfma_f32_16x16x32_bf16 v[92:95], v[128:131], v[218:221], v[92:95]
	v_mfma_f32_16x16x32_bf16 v[88:91], v[136:139], v[218:221], v[88:91]
	v_mfma_f32_16x16x32_bf16 v[76:79], v[128:131], v[226:229], v[76:79]
	v_mfma_f32_16x16x32_bf16 v[72:75], v[136:139], v[226:229], v[72:75]
	v_mfma_f32_16x16x32_bf16 v[124:127], v[132:135], v[192:195], v[124:127]
	v_mfma_f32_16x16x32_bf16 v[120:123], v[140:143], v[192:195], v[120:123]
	v_mfma_f32_16x16x32_bf16 v[112:115], v[132:135], v[200:203], v[112:115]
	v_mfma_f32_16x16x32_bf16 v[104:107], v[140:143], v[200:203], v[104:107]
	v_mfma_f32_16x16x32_bf16 v[92:95], v[132:135], v[222:225], v[92:95]
	v_mfma_f32_16x16x32_bf16 v[88:91], v[140:143], v[222:225], v[88:91]
	v_mfma_f32_16x16x32_bf16 v[76:79], v[132:135], v[230:233], v[76:79]
	v_mfma_f32_16x16x32_bf16 v[72:75], v[140:143], v[230:233], v[72:75]
	v_mfma_f32_16x16x32_bf16 v[116:119], v[164:167], v[188:191], v[116:119]
	v_mfma_f32_16x16x32_bf16 v[108:111], v[180:183], v[188:191], v[108:111]
	v_mfma_f32_16x16x32_bf16 v[100:103], v[164:167], v[196:199], v[100:103]
	v_mfma_f32_16x16x32_bf16 v[96:99], v[180:183], v[196:199], v[96:99]
	v_mfma_f32_16x16x32_bf16 v[84:87], v[164:167], v[218:221], v[84:87]
	v_mfma_f32_16x16x32_bf16 v[80:83], v[180:183], v[218:221], v[80:83]
	v_mfma_f32_16x16x32_bf16 v[68:71], v[164:167], v[226:229], v[68:71]
	v_mfma_f32_16x16x32_bf16 v[64:67], v[180:183], v[226:229], v[64:67]
	v_mfma_f32_16x16x32_bf16 v[116:119], v[168:171], v[192:195], v[116:119]
	v_mfma_f32_16x16x32_bf16 v[108:111], v[184:187], v[192:195], v[108:111]
	v_mfma_f32_16x16x32_bf16 v[100:103], v[168:171], v[200:203], v[100:103]
	v_mfma_f32_16x16x32_bf16 v[96:99], v[184:187], v[200:203], v[96:99]
	v_mfma_f32_16x16x32_bf16 v[84:87], v[168:171], v[222:225], v[84:87]
	v_mfma_f32_16x16x32_bf16 v[80:83], v[184:187], v[222:225], v[80:83]
	v_mfma_f32_16x16x32_bf16 v[68:71], v[168:171], v[230:233], v[68:71]
	v_mfma_f32_16x16x32_bf16 v[64:67], v[184:187], v[230:233], v[64:67]
	s_setprio 0
	s_barrier
	s_add_i32 s14, s16, s6
	v_lshl_add_u64 v[172:173], s[46:47], 0, v[152:153]
	s_mov_b32 m0, s14
	ds_read_b128 v[188:191], v178 offset:16384
	ds_read_b128 v[192:195], v178 offset:17408
	ds_read_b128 v[196:199], v178 offset:18432
	ds_read_b128 v[200:203], v178 offset:19456
	ds_read_b128 v[218:221], v178 offset:20480
	ds_read_b128 v[222:225], v178 offset:21504
	ds_read_b128 v[226:229], v178 offset:22528
	ds_read_b128 v[230:233], v178 offset:23552
	global_load_lds_dwordx4 v[172:173], off
	s_add_i32 m0, s14, 0x2000
	s_add_u32 s14, s46, 0x100000
	v_lshl_add_u64 v[204:205], s[46:47], 0, v[144:145]
	s_addc_u32 s15, s47, 0
	s_add_i32 s16, s17, s6
	global_load_lds_dwordx4 v[204:205], off
	s_waitcnt vmcnt(4)
	s_waitcnt lgkmcnt(0)
	s_barrier
; #define PG8_STAGE(bufoff, gbase, voff) do { _Pragma("unroll") for (int _i = 0; _i < 2; ++_i) \
;         __builtin_amdgcn_global_load_lds((const unsigned*)((const char*)(gbase) + (voff)[_i]), (LAS unsigned*)(lds + (bufoff) + ldsw + _i * 8192), 16, 0, 0); } while (0)
; #define PG8_LDA(dst, b, h) do { _Pragma("unroll") for (int m = 0; m < 4; ++m) _Pragma("unroll") for (int k = 0; k < 2; ++k) dst[m][k] = *(const LAS bf16x8*)(lds + PG8_SA(b, h) + aoff + m * 2048 + k * 1024); } while (0)
; #define PG8_LDB(dst, b, h) do { _Pragma("unroll") for (int n = 0; n < 2; ++n) _Pragma("unroll") for (int k = 0; k < 2; ++k) dst[n][k] = *(const LAS bf16x8*)(lds + PG8_SB(b, h) + boff + n * 2048 + k * 1024); } while (0)
; #define PG8_MMA(ai, bj, At, Bt) do { __builtin_amdgcn_s_setprio(1); _Pragma("unroll") for (int m = 0; m < 4; ++m) _Pragma("unroll") for (int n = 0; n < 2; ++n) _Pragma("unroll") for (int k = 0; k < 2; ++k) \
;         acc[ai][bj][m][n] = __builtin_amdgcn_mfma_f32_16x16x32_bf16(Bt[n][k], At[m][k], acc[ai][bj][m][n], 0, 0, 0); __builtin_amdgcn_s_setprio(0); } while (0)
; #define PG8_WAIT_V(n) asm volatile("s_waitcnt vmcnt(" #n ")" ::: "memory")
; #define PG8_WAIT_L(n) asm volatile("s_waitcnt lgkmcnt(" #n ")" ::: "memory")
; #define PG8_BAR __builtin_amdgcn_s_barrier()
; #define PG8_SCHED __builtin_amdgcn_sched_barrier(0)
; template <class Epi, class Sched, bool ALIGN_EPI = false, bool SP2 = false>
; __device__ __forceinline__ void gemm_phase(LAS unsigned char* lds, const Gemm g, const Sched& S, const Epi& E) {
;     ...
;             PG8_WAIT_V(8); PG8_WAIT_L(0); PG8_BAR; PG8_MMA(1, 0, At, B0); PG8_MMA(1, 1, At, B1); PG8_BAR; PG8_SCHED;
;             PG8_LDB(B0, 1, 0); PG8_LDB(B1, 1, 1); PG8_SCHED; PG8_LDA(At, 1, 0); PG8_STAGE(PG8_SA(0, 1), a2 + hstep, voffA);
;             PG8_WAIT_V(8); PG8_WAIT_L(0); PG8_BAR; PG8_MMA(0, 0, At, B0); PG8_MMA(0, 1, At, B1); PG8_BAR; PG8_SCHED;
	s_setprio 1
	s_waitcnt lgkmcnt(0)
	v_mfma_f32_16x16x32_bf16 v[60:63], v[128:131], v[188:191], v[60:63]
	v_mfma_f32_16x16x32_bf16 v[56:59], v[136:139], v[188:191], v[56:59]
	v_mfma_f32_16x16x32_bf16 v[44:47], v[128:131], v[196:199], v[44:47]
	v_lshl_add_u64 v[234:235], s[14:15], 0, v[152:153]
	s_mov_b32 m0, s16
	v_lshl_add_u64 v[236:237], s[48:49], 0, v[146:147]
	v_mfma_f32_16x16x32_bf16 v[40:43], v[136:139], v[196:199], v[40:43]
	global_load_lds_dwordx4 v[234:235], off
	v_mfma_f32_16x16x32_bf16 v[28:31], v[128:131], v[218:221], v[28:31]
	v_mfma_f32_16x16x32_bf16 v[24:27], v[136:139], v[218:221], v[24:27]
	v_mfma_f32_16x16x32_bf16 v[12:15], v[128:131], v[226:229], v[12:15]
	v_mfma_f32_16x16x32_bf16 v[8:11], v[136:139], v[226:229], v[8:11]
	v_mfma_f32_16x16x32_bf16 v[60:63], v[132:135], v[192:195], v[60:63]
	v_mfma_f32_16x16x32_bf16 v[56:59], v[140:143], v[192:195], v[56:59]
	v_lshl_add_u64 v[234:235], s[14:15], 0, v[144:145]
	s_add_i32 m0, s16, 0x2000
	v_mfma_f32_16x16x32_bf16 v[44:47], v[132:135], v[200:203], v[44:47]
	global_load_lds_dwordx4 v[234:235], off
	v_mfma_f32_16x16x32_bf16 v[40:43], v[140:143], v[200:203], v[40:43]
	v_mfma_f32_16x16x32_bf16 v[28:31], v[132:135], v[222:225], v[28:31]
	v_mfma_f32_16x16x32_bf16 v[24:27], v[140:143], v[222:225], v[24:27]
	v_mfma_f32_16x16x32_bf16 v[12:15], v[132:135], v[230:233], v[12:15]
	v_mfma_f32_16x16x32_bf16 v[8:11], v[140:143], v[230:233], v[8:11]
	v_mfma_f32_16x16x32_bf16 v[52:55], v[164:167], v[188:191], v[52:55]
	v_mfma_f32_16x16x32_bf16 v[48:51], v[180:183], v[188:191], v[48:51]
	v_lshl_add_u64 v[234:235], s[48:49], 0, v[148:149]
	s_mov_b32 m0, s7
	v_mfma_f32_16x16x32_bf16 v[36:39], v[164:167], v[196:199], v[36:39]
	global_load_lds_dwordx4 v[234:235], off
	v_mfma_f32_16x16x32_bf16 v[32:35], v[180:183], v[196:199], v[32:35]
	v_mfma_f32_16x16x32_bf16 v[20:23], v[164:167], v[218:221], v[20:23]
	v_mfma_f32_16x16x32_bf16 v[16:19], v[180:183], v[218:221], v[16:19]
	v_mfma_f32_16x16x32_bf16 v[4:7], v[164:167], v[226:229], v[4:7]
	v_mfma_f32_16x16x32_bf16 v[0:3], v[180:183], v[226:229], v[0:3]
	v_mfma_f32_16x16x32_bf16 v[52:55], v[168:171], v[192:195], v[52:55]
	v_mfma_f32_16x16x32_bf16 v[48:51], v[184:187], v[192:195], v[48:51]
	s_mov_b32 m0, s8
	v_mfma_f32_16x16x32_bf16 v[36:39], v[168:171], v[200:203], v[36:39]
	global_load_lds_dwordx4 v[236:237], off
	v_mfma_f32_16x16x32_bf16 v[32:35], v[184:187], v[200:203], v[32:35]
	v_mfma_f32_16x16x32_bf16 v[20:23], v[168:171], v[222:225], v[20:23]
	v_mfma_f32_16x16x32_bf16 v[16:19], v[184:187], v[222:225], v[16:19]
	v_mfma_f32_16x16x32_bf16 v[4:7], v[168:171], v[230:233], v[4:7]
	v_mfma_f32_16x16x32_bf16 v[0:3], v[184:187], v[230:233], v[0:3]
	s_setprio 0
	s_barrier
	s_add_i32 s16, 0, 0x18000
	s_add_i32 s17, 0, 0x1c000
	v_add_u32_e32 v140, s16, v175
	v_add_u32_e32 v179, s17, v175
	ds_read_b128 v[128:131], v140
	ds_read_b128 v[132:135], v140 offset:1024
	ds_read_b128 v[136:139], v140 offset:2048
	ds_read_b128 v[140:143], v140 offset:3072
	ds_read_b128 v[164:167], v179
	ds_read_b128 v[168:171], v179 offset:1024
	ds_read_b128 v[180:183], v179 offset:2048
	ds_read_b128 v[184:187], v179 offset:3072
	s_add_u32 s14, s48, 0x100000
	s_addc_u32 s15, s49, 0
	s_mov_b32 m0, s9
	v_lshl_add_u64 v[238:239], s[14:15], 0, v[148:149]
	ds_read_b128 v[188:191], v178 offset:32768
	ds_read_b128 v[192:195], v178 offset:33792
	ds_read_b128 v[196:199], v178 offset:34816
	ds_read_b128 v[200:203], v178 offset:35840
	ds_read_b128 v[218:221], v178 offset:36864
	ds_read_b128 v[222:225], v178 offset:37888
	ds_read_b128 v[226:229], v178 offset:38912
	ds_read_b128 v[230:233], v178 offset:39936
	global_load_lds_dwordx4 v[238:239], off
	v_lshl_add_u64 v[238:239], s[14:15], 0, v[146:147]
	s_mov_b32 m0, s10
	s_nop 0
	global_load_lds_dwordx4 v[238:239], off
	s_waitcnt vmcnt(8)
	s_waitcnt lgkmcnt(0)
	s_barrier
; #define PG8_STAGE(bufoff, gbase, voff) do { _Pragma("unroll") for (int _i = 0; _i < 2; ++_i) \
;         __builtin_amdgcn_global_load_lds((const unsigned*)((const char*)(gbase) + (voff)[_i]), (LAS unsigned*)(lds + (bufoff) + ldsw + _i * 8192), 16, 0, 0); } while (0)
; #define PG8_LDA(dst, b, h) do { _Pragma("unroll") for (int m = 0; m < 4; ++m) _Pragma("unroll") for (int k = 0; k < 2; ++k) dst[m][k] = *(const LAS bf16x8*)(lds + PG8_SA(b, h) + aoff + m * 2048 + k * 1024); } while (0)
; #define PG8_MMA(ai, bj, At, Bt) do { __builtin_amdgcn_s_setprio(1); _Pragma("unroll") for (int m = 0; m < 4; ++m) _Pragma("unroll") for (int n = 0; n < 2; ++n) _Pragma("unroll") for (int k = 0; k < 2; ++k) \
;         acc[ai][bj][m][n] = __builtin_amdgcn_mfma_f32_16x16x32_bf16(Bt[n][k], At[m][k], acc[ai][bj][m][n], 0, 0, 0); __builtin_amdgcn_s_setprio(0); } while (0)
; #define PG8_WAIT_V(n) asm volatile("s_waitcnt vmcnt(" #n ")" ::: "memory")
; #define PG8_WAIT_L(n) asm volatile("s_waitcnt lgkmcnt(" #n ")" ::: "memory")
; #define PG8_BAR __builtin_amdgcn_s_barrier()
; #define PG8_SCHED __builtin_amdgcn_sched_barrier(0)
; template <class Epi, class Sched, bool ALIGN_EPI = false, bool SP2 = false>
; __device__ __forceinline__ void gemm_phase(LAS unsigned char* lds, const Gemm g, const Sched& S, const Epi& E) {
;     ...
;             PG8_WAIT_V(8); PG8_WAIT_L(0); PG8_BAR; PG8_MMA(0, 0, At, B0); PG8_MMA(0, 1, At, B1); PG8_BAR; PG8_SCHED;
;             PG8_LDA(At, 1, 1); PG8_STAGE(PG8_SB(1, 0), b3, voffB); PG8_STAGE(PG8_SB(1, 1), b3 + hstep, voffB); PG8_STAGE(PG8_SA(1, 0), a3, voffA);
;             PG8_WAIT_V(8); PG8_WAIT_L(0); PG8_BAR; PG8_MMA(1, 0, At, B0); PG8_MMA(1, 1, At, B1); PG8_BAR; PG8_SCHED;
;     ...
;         if constexpr (ALIGN_EPI) { if (wr == 0) PG8_BAR; }
	s_setprio 1
	s_waitcnt lgkmcnt(0)
	v_mfma_f32_16x16x32_bf16 v[124:127], v[128:131], v[188:191], v[124:127]
	v_mfma_f32_16x16x32_bf16 v[120:123], v[136:139], v[188:191], v[120:123]
	v_mfma_f32_16x16x32_bf16 v[112:115], v[128:131], v[196:199], v[112:115]
	v_mfma_f32_16x16x32_bf16 v[104:107], v[136:139], v[196:199], v[104:107]
	v_mfma_f32_16x16x32_bf16 v[92:95], v[128:131], v[218:221], v[92:95]
	v_mfma_f32_16x16x32_bf16 v[88:91], v[136:139], v[218:221], v[88:91]
	v_mfma_f32_16x16x32_bf16 v[76:79], v[128:131], v[226:229], v[76:79]
	v_mfma_f32_16x16x32_bf16 v[72:75], v[136:139], v[226:229], v[72:75]
	v_mfma_f32_16x16x32_bf16 v[124:127], v[132:135], v[192:195], v[124:127]
	v_mfma_f32_16x16x32_bf16 v[120:123], v[140:143], v[192:195], v[120:123]
	v_mfma_f32_16x16x32_bf16 v[112:115], v[132:135], v[200:203], v[112:115]
	v_mfma_f32_16x16x32_bf16 v[104:107], v[140:143], v[200:203], v[104:107]
	v_mfma_f32_16x16x32_bf16 v[92:95], v[132:135], v[222:225], v[92:95]
	v_mfma_f32_16x16x32_bf16 v[88:91], v[140:143], v[222:225], v[88:91]
	v_mfma_f32_16x16x32_bf16 v[76:79], v[132:135], v[230:233], v[76:79]
	v_mfma_f32_16x16x32_bf16 v[72:75], v[140:143], v[230:233], v[72:75]
	v_mfma_f32_16x16x32_bf16 v[116:119], v[164:167], v[188:191], v[116:119]
	v_mfma_f32_16x16x32_bf16 v[108:111], v[180:183], v[188:191], v[108:111]
	v_mfma_f32_16x16x32_bf16 v[100:103], v[164:167], v[196:199], v[100:103]
	v_mfma_f32_16x16x32_bf16 v[96:99], v[180:183], v[196:199], v[96:99]
	v_mfma_f32_16x16x32_bf16 v[84:87], v[164:167], v[218:221], v[84:87]
	v_mfma_f32_16x16x32_bf16 v[80:83], v[180:183], v[218:221], v[80:83]
	v_mfma_f32_16x16x32_bf16 v[68:71], v[164:167], v[226:229], v[68:71]
	v_mfma_f32_16x16x32_bf16 v[64:67], v[180:183], v[226:229], v[64:67]
	v_mfma_f32_16x16x32_bf16 v[116:119], v[168:171], v[192:195], v[116:119]
	v_mfma_f32_16x16x32_bf16 v[108:111], v[184:187], v[192:195], v[108:111]
	v_mfma_f32_16x16x32_bf16 v[100:103], v[168:171], v[200:203], v[100:103]
	v_mfma_f32_16x16x32_bf16 v[96:99], v[184:187], v[200:203], v[96:99]
	v_mfma_f32_16x16x32_bf16 v[84:87], v[168:171], v[222:225], v[84:87]
	v_mfma_f32_16x16x32_bf16 v[80:83], v[184:187], v[222:225], v[80:83]
	v_mfma_f32_16x16x32_bf16 v[68:71], v[168:171], v[230:233], v[68:71]
	v_mfma_f32_16x16x32_bf16 v[64:67], v[184:187], v[230:233], v[64:67]
	s_setprio 0
	s_barrier
	s_add_i32 s14, s16, s6
	v_lshl_add_u64 v[172:173], v[172:173], 0, s[30:31]
	s_mov_b32 m0, s14
	ds_read_b128 v[188:191], v178 offset:49152
	ds_read_b128 v[192:195], v178 offset:50176
	ds_read_b128 v[196:199], v178 offset:51200
	ds_read_b128 v[200:203], v178 offset:52224
	ds_read_b128 v[218:221], v178 offset:53248
	ds_read_b128 v[222:225], v178 offset:54272
	ds_read_b128 v[226:229], v178 offset:55296
	ds_read_b128 v[230:233], v178 offset:56320
	global_load_lds_dwordx4 v[172:173], off
	s_add_i32 m0, s14, 0x2000
	s_add_u32 s14, s46, 0x100080
	v_lshl_add_u64 v[172:173], v[204:205], 0, s[30:31]
	s_addc_u32 s15, s47, 0
	s_add_i32 s16, s17, s6
	global_load_lds_dwordx4 v[172:173], off
	s_waitcnt vmcnt(4)
	s_waitcnt lgkmcnt(0)
	s_barrier
	s_setprio 1
	s_waitcnt lgkmcnt(0)
	v_mfma_f32_16x16x32_bf16 v[60:63], v[128:131], v[188:191], v[60:63]
	v_mfma_f32_16x16x32_bf16 v[56:59], v[136:139], v[188:191], v[56:59]
	v_mfma_f32_16x16x32_bf16 v[44:47], v[128:131], v[196:199], v[44:47]
	v_lshl_add_u64 v[172:173], s[14:15], 0, v[152:153]
	s_mov_b32 m0, s16
	v_mfma_f32_16x16x32_bf16 v[40:43], v[136:139], v[196:199], v[40:43]
	global_load_lds_dwordx4 v[172:173], off
	v_mfma_f32_16x16x32_bf16 v[28:31], v[128:131], v[218:221], v[28:31]
	v_mfma_f32_16x16x32_bf16 v[24:27], v[136:139], v[218:221], v[24:27]
	v_mfma_f32_16x16x32_bf16 v[12:15], v[128:131], v[226:229], v[12:15]
	v_mfma_f32_16x16x32_bf16 v[8:11], v[136:139], v[226:229], v[8:11]
	v_mfma_f32_16x16x32_bf16 v[60:63], v[132:135], v[192:195], v[60:63]
	v_mfma_f32_16x16x32_bf16 v[56:59], v[140:143], v[192:195], v[56:59]
	v_lshl_add_u64 v[172:173], s[14:15], 0, v[144:145]
	s_add_i32 m0, s16, 0x2000
	v_mfma_f32_16x16x32_bf16 v[44:47], v[132:135], v[200:203], v[44:47]
	global_load_lds_dwordx4 v[172:173], off
	v_mfma_f32_16x16x32_bf16 v[40:43], v[140:143], v[200:203], v[40:43]
	v_mfma_f32_16x16x32_bf16 v[28:31], v[132:135], v[222:225], v[28:31]
	v_mfma_f32_16x16x32_bf16 v[24:27], v[140:143], v[222:225], v[24:27]
	v_mfma_f32_16x16x32_bf16 v[12:15], v[132:135], v[230:233], v[12:15]
	v_mfma_f32_16x16x32_bf16 v[8:11], v[140:143], v[230:233], v[8:11]
	v_mfma_f32_16x16x32_bf16 v[52:55], v[164:167], v[188:191], v[52:55]
	v_mfma_f32_16x16x32_bf16 v[48:51], v[180:183], v[188:191], v[48:51]
	v_lshl_add_u64 v[172:173], v[234:235], 0, s[30:31]
	s_mov_b32 m0, s12
	v_mfma_f32_16x16x32_bf16 v[36:39], v[164:167], v[196:199], v[36:39]
	global_load_lds_dwordx4 v[172:173], off
	v_mfma_f32_16x16x32_bf16 v[32:35], v[180:183], v[196:199], v[32:35]
	v_mfma_f32_16x16x32_bf16 v[20:23], v[164:167], v[218:221], v[20:23]
	v_mfma_f32_16x16x32_bf16 v[16:19], v[180:183], v[218:221], v[16:19]
	v_mfma_f32_16x16x32_bf16 v[4:7], v[164:167], v[226:229], v[4:7]
	v_mfma_f32_16x16x32_bf16 v[0:3], v[180:183], v[226:229], v[0:3]
	v_mfma_f32_16x16x32_bf16 v[52:55], v[168:171], v[192:195], v[52:55]
	v_mfma_f32_16x16x32_bf16 v[48:51], v[184:187], v[192:195], v[48:51]
	v_lshl_add_u64 v[172:173], v[236:237], 0, s[30:31]
	s_mov_b32 m0, s13
	v_mfma_f32_16x16x32_bf16 v[36:39], v[168:171], v[200:203], v[36:39]
	global_load_lds_dwordx4 v[172:173], off
	v_mfma_f32_16x16x32_bf16 v[32:35], v[184:187], v[200:203], v[32:35]
	v_mfma_f32_16x16x32_bf16 v[20:23], v[168:171], v[222:225], v[20:23]
	v_mfma_f32_16x16x32_bf16 v[16:19], v[184:187], v[222:225], v[16:19]
	v_mfma_f32_16x16x32_bf16 v[4:7], v[168:171], v[230:233], v[4:7]
	v_mfma_f32_16x16x32_bf16 v[0:3], v[184:187], v[230:233], v[0:3]
	s_setprio 0
	s_barrier
	s_add_i32 s71, s71, 2
	s_add_u32 s42, s42, 0x100
	s_addc_u32 s43, s43, 0
	s_add_u32 s64, s64, 0x100
	s_addc_u32 s65, s65, 0
	s_cmp_gt_u32 s71, 61
	s_cbranch_scc0 .LBB0_612
	s_and_b64 vcc, exec, s[26:27]
	s_cbranch_vccz .LBB0_615
	s_barrier
